# GEMM K-loops: LDS-DMA loads use the SGPR-base form (16 64-bit VALU address adds per iteration removed), on top of no-setprio + DPP epilogue + pipelined final norm
# baseline (speedup 1.0000x reference)
.LBB0_577:
	ds_read_b128 v[128:131], v193
	ds_read_b128 v[132:135], v193 offset:1024
	ds_read_b128 v[136:139], v193 offset:2048
	ds_read_b128 v[140:143], v193 offset:3072
	ds_read_b128 v[144:147], v194
	ds_read_b128 v[148:151], v194 offset:1024
	ds_read_b128 v[152:155], v194 offset:2048
	ds_read_b128 v[156:159], v194 offset:3072
	s_add_u32 s35, s42, 0xfff80080
	s_addc_u32 s39, s43, -1
	s_cmp_eq_u32 s31, 4
	s_cselect_b32 s47, s1, s39
	s_cselect_b32 s46, s0, s35
	s_cselect_b32 s45, s37, s23
	s_cselect_b32 s44, s36, s11
	s_add_i32 m0, s7, 0xc000
	ds_read_b128 v[176:179], v195
	ds_read_b128 v[180:183], v195 offset:1024
	ds_read_b128 v[184:187], v195 offset:2048
	ds_read_b128 v[198:201], v195 offset:3072
	ds_read_b128 v[202:205], v195 offset:4096
	ds_read_b128 v[206:209], v195 offset:5120
	ds_read_b128 v[210:213], v195 offset:6144
	ds_read_b128 v[214:217], v195 offset:7168
	global_load_lds_dwordx4 v168, s[42:43]
	s_add_i32 m0, s7, 0xe000
	s_nop 0
	global_load_lds_dwordx4 v170, s[42:43]
	s_waitcnt vmcnt(8)
	s_waitcnt lgkmcnt(0)
	s_barrier
	s_waitcnt lgkmcnt(0)
	v_mfma_f32_16x16x32_bf16 v[124:127], v[128:131], v[176:179], v[124:127]
	v_mfma_f32_16x16x32_bf16 v[120:123], v[136:139], v[176:179], v[120:123]
	v_mfma_f32_16x16x32_bf16 v[108:111], v[128:131], v[184:187], v[108:111]
	v_mfma_f32_16x16x32_bf16 v[104:107], v[136:139], v[184:187], v[104:107]
	v_mfma_f32_16x16x32_bf16 v[92:95], v[128:131], v[202:205], v[92:95]
	v_mfma_f32_16x16x32_bf16 v[88:91], v[136:139], v[202:205], v[88:91]
	v_mfma_f32_16x16x32_bf16 v[76:79], v[128:131], v[210:213], v[76:79]
	v_mfma_f32_16x16x32_bf16 v[72:75], v[136:139], v[210:213], v[72:75]
	v_mfma_f32_16x16x32_bf16 v[124:127], v[132:135], v[180:183], v[124:127]
	v_mfma_f32_16x16x32_bf16 v[120:123], v[140:143], v[180:183], v[120:123]
	v_mfma_f32_16x16x32_bf16 v[108:111], v[132:135], v[198:201], v[108:111]
	v_mfma_f32_16x16x32_bf16 v[104:107], v[140:143], v[198:201], v[104:107]
	v_mfma_f32_16x16x32_bf16 v[92:95], v[132:135], v[206:209], v[92:95]
	v_mfma_f32_16x16x32_bf16 v[88:91], v[140:143], v[206:209], v[88:91]
	v_mfma_f32_16x16x32_bf16 v[76:79], v[132:135], v[214:217], v[76:79]
	v_mfma_f32_16x16x32_bf16 v[72:75], v[140:143], v[214:217], v[72:75]
	v_mfma_f32_16x16x32_bf16 v[116:119], v[144:147], v[176:179], v[116:119]
	v_mfma_f32_16x16x32_bf16 v[112:115], v[152:155], v[176:179], v[112:115]
	v_mfma_f32_16x16x32_bf16 v[100:103], v[144:147], v[184:187], v[100:103]
	v_mfma_f32_16x16x32_bf16 v[96:99], v[152:155], v[184:187], v[96:99]
	v_mfma_f32_16x16x32_bf16 v[84:87], v[144:147], v[202:205], v[84:87]
	v_mfma_f32_16x16x32_bf16 v[80:83], v[152:155], v[202:205], v[80:83]
	v_mfma_f32_16x16x32_bf16 v[68:71], v[144:147], v[210:213], v[68:71]
	v_mfma_f32_16x16x32_bf16 v[64:67], v[152:155], v[210:213], v[64:67]
	v_mfma_f32_16x16x32_bf16 v[116:119], v[148:151], v[180:183], v[116:119]
	v_mfma_f32_16x16x32_bf16 v[112:115], v[156:159], v[180:183], v[112:115]
	v_mfma_f32_16x16x32_bf16 v[100:103], v[148:151], v[198:201], v[100:103]
	v_mfma_f32_16x16x32_bf16 v[96:99], v[156:159], v[198:201], v[96:99]
	v_mfma_f32_16x16x32_bf16 v[84:87], v[148:151], v[206:209], v[84:87]
	v_mfma_f32_16x16x32_bf16 v[80:83], v[156:159], v[206:209], v[80:83]
	v_mfma_f32_16x16x32_bf16 v[68:71], v[148:151], v[214:217], v[68:71]
	v_mfma_f32_16x16x32_bf16 v[64:67], v[156:159], v[214:217], v[64:67]
	s_barrier
	s_add_i32 s35, s48, s6
	s_mov_b32 m0, s35
	ds_read_b128 v[176:179], v195 offset:16384
	ds_read_b128 v[180:183], v195 offset:17408
	ds_read_b128 v[184:187], v195 offset:18432
	ds_read_b128 v[198:201], v195 offset:19456
	ds_read_b128 v[202:205], v195 offset:20480
	ds_read_b128 v[206:209], v195 offset:21504
	ds_read_b128 v[210:213], v195 offset:22528
	ds_read_b128 v[214:217], v195 offset:23552
	global_load_lds_dwordx4 v162, s[44:45]
	s_add_i32 m0, s35, 0x2000
	s_add_u32 s50, s44, 0x20000
	s_addc_u32 s51, s45, 0
	s_add_i32 s35, s49, s6
	global_load_lds_dwordx4 v166, s[44:45]
	s_mov_b32 m0, s35
	s_nop 0
	global_load_lds_dwordx4 v162, s[50:51]
	s_add_i32 m0, s35, 0x2000
	s_nop 0
	global_load_lds_dwordx4 v166, s[50:51]
	s_mov_b32 m0, s7
	s_nop 0
	global_load_lds_dwordx4 v160, s[46:47]
	s_mov_b32 m0, s8
	s_nop 0
	global_load_lds_dwordx4 v164, s[46:47]
	s_waitcnt vmcnt(8)
	s_waitcnt lgkmcnt(0)
	s_barrier
	s_waitcnt lgkmcnt(0)
	v_mfma_f32_16x16x32_bf16 v[60:63], v[128:131], v[176:179], v[60:63]
	v_mfma_f32_16x16x32_bf16 v[56:59], v[136:139], v[176:179], v[56:59]
	v_mfma_f32_16x16x32_bf16 v[44:47], v[128:131], v[184:187], v[44:47]
	v_mfma_f32_16x16x32_bf16 v[40:43], v[136:139], v[184:187], v[40:43]
	v_mfma_f32_16x16x32_bf16 v[28:31], v[128:131], v[202:205], v[28:31]
	v_mfma_f32_16x16x32_bf16 v[24:27], v[136:139], v[202:205], v[24:27]
	v_mfma_f32_16x16x32_bf16 v[12:15], v[128:131], v[210:213], v[12:15]
	v_mfma_f32_16x16x32_bf16 v[8:11], v[136:139], v[210:213], v[8:11]
	v_mfma_f32_16x16x32_bf16 v[60:63], v[132:135], v[180:183], v[60:63]
	v_mfma_f32_16x16x32_bf16 v[56:59], v[140:143], v[180:183], v[56:59]
	v_mfma_f32_16x16x32_bf16 v[44:47], v[132:135], v[198:201], v[44:47]
	v_mfma_f32_16x16x32_bf16 v[40:43], v[140:143], v[198:201], v[40:43]
	v_mfma_f32_16x16x32_bf16 v[28:31], v[132:135], v[206:209], v[28:31]
	v_mfma_f32_16x16x32_bf16 v[24:27], v[140:143], v[206:209], v[24:27]
	v_mfma_f32_16x16x32_bf16 v[12:15], v[132:135], v[214:217], v[12:15]
	v_mfma_f32_16x16x32_bf16 v[8:11], v[140:143], v[214:217], v[8:11]
	v_mfma_f32_16x16x32_bf16 v[52:55], v[144:147], v[176:179], v[52:55]
	v_mfma_f32_16x16x32_bf16 v[48:51], v[152:155], v[176:179], v[48:51]
	v_mfma_f32_16x16x32_bf16 v[36:39], v[144:147], v[184:187], v[36:39]
	v_mfma_f32_16x16x32_bf16 v[32:35], v[152:155], v[184:187], v[32:35]
	v_mfma_f32_16x16x32_bf16 v[20:23], v[144:147], v[202:205], v[20:23]
	v_mfma_f32_16x16x32_bf16 v[16:19], v[152:155], v[202:205], v[16:19]
	v_mfma_f32_16x16x32_bf16 v[4:7], v[144:147], v[210:213], v[4:7]
	v_mfma_f32_16x16x32_bf16 v[0:3], v[152:155], v[210:213], v[0:3]
	v_mfma_f32_16x16x32_bf16 v[52:55], v[148:151], v[180:183], v[52:55]
	v_mfma_f32_16x16x32_bf16 v[48:51], v[156:159], v[180:183], v[48:51]
	v_mfma_f32_16x16x32_bf16 v[36:39], v[148:151], v[198:201], v[36:39]
	v_mfma_f32_16x16x32_bf16 v[32:35], v[156:159], v[198:201], v[32:35]
	v_mfma_f32_16x16x32_bf16 v[20:23], v[148:151], v[206:209], v[20:23]
	v_mfma_f32_16x16x32_bf16 v[16:19], v[156:159], v[206:209], v[16:19]
	v_mfma_f32_16x16x32_bf16 v[4:7], v[148:151], v[214:217], v[4:7]
	v_mfma_f32_16x16x32_bf16 v[0:3], v[156:159], v[214:217], v[0:3]
	s_barrier
	s_add_i32 s35, 0, 0x18000
	s_add_i32 s39, 0, 0x1c000
	v_add_u32_e32 v140, s35, v191
	v_add_u32_e32 v156, s39, v191
	ds_read_b128 v[128:131], v140
	ds_read_b128 v[132:135], v140 offset:1024
	ds_read_b128 v[136:139], v140 offset:2048
	ds_read_b128 v[140:143], v140 offset:3072
	ds_read_b128 v[144:147], v156
	ds_read_b128 v[148:151], v156 offset:1024
	ds_read_b128 v[152:155], v156 offset:2048
	ds_read_b128 v[156:159], v156 offset:3072
	s_add_u32 s46, s46, 0x80000
	s_addc_u32 s47, s47, 0
	s_mov_b32 m0, s9
	ds_read_b128 v[176:179], v195 offset:32768
	ds_read_b128 v[180:183], v195 offset:33792
	ds_read_b128 v[184:187], v195 offset:34816
	ds_read_b128 v[198:201], v195 offset:35840
	ds_read_b128 v[202:205], v195 offset:36864
	ds_read_b128 v[206:209], v195 offset:37888
	ds_read_b128 v[210:213], v195 offset:38912
	ds_read_b128 v[214:217], v195 offset:39936
	global_load_lds_dwordx4 v160, s[46:47]
	s_mov_b32 m0, s24
	s_nop 0
	global_load_lds_dwordx4 v164, s[46:47]
	s_waitcnt vmcnt(8)
	s_waitcnt lgkmcnt(0)
	s_barrier
	s_waitcnt lgkmcnt(0)
	v_mfma_f32_16x16x32_bf16 v[124:127], v[128:131], v[176:179], v[124:127]
	v_mfma_f32_16x16x32_bf16 v[120:123], v[136:139], v[176:179], v[120:123]
	v_mfma_f32_16x16x32_bf16 v[108:111], v[128:131], v[184:187], v[108:111]
	v_mfma_f32_16x16x32_bf16 v[104:107], v[136:139], v[184:187], v[104:107]
	v_mfma_f32_16x16x32_bf16 v[92:95], v[128:131], v[202:205], v[92:95]
	v_mfma_f32_16x16x32_bf16 v[88:91], v[136:139], v[202:205], v[88:91]
	v_mfma_f32_16x16x32_bf16 v[76:79], v[128:131], v[210:213], v[76:79]
	v_mfma_f32_16x16x32_bf16 v[72:75], v[136:139], v[210:213], v[72:75]
	v_mfma_f32_16x16x32_bf16 v[124:127], v[132:135], v[180:183], v[124:127]
	v_mfma_f32_16x16x32_bf16 v[120:123], v[140:143], v[180:183], v[120:123]
	v_mfma_f32_16x16x32_bf16 v[108:111], v[132:135], v[198:201], v[108:111]
	v_mfma_f32_16x16x32_bf16 v[104:107], v[140:143], v[198:201], v[104:107]
	v_mfma_f32_16x16x32_bf16 v[92:95], v[132:135], v[206:209], v[92:95]
	v_mfma_f32_16x16x32_bf16 v[88:91], v[140:143], v[206:209], v[88:91]
	v_mfma_f32_16x16x32_bf16 v[76:79], v[132:135], v[214:217], v[76:79]
	v_mfma_f32_16x16x32_bf16 v[72:75], v[140:143], v[214:217], v[72:75]
	v_mfma_f32_16x16x32_bf16 v[116:119], v[144:147], v[176:179], v[116:119]
	v_mfma_f32_16x16x32_bf16 v[112:115], v[152:155], v[176:179], v[112:115]
	v_mfma_f32_16x16x32_bf16 v[100:103], v[144:147], v[184:187], v[100:103]
	v_mfma_f32_16x16x32_bf16 v[96:99], v[152:155], v[184:187], v[96:99]
	v_mfma_f32_16x16x32_bf16 v[84:87], v[144:147], v[202:205], v[84:87]
	v_mfma_f32_16x16x32_bf16 v[80:83], v[152:155], v[202:205], v[80:83]
	v_mfma_f32_16x16x32_bf16 v[68:71], v[144:147], v[210:213], v[68:71]
	v_mfma_f32_16x16x32_bf16 v[64:67], v[152:155], v[210:213], v[64:67]
	v_mfma_f32_16x16x32_bf16 v[116:119], v[148:151], v[180:183], v[116:119]
	v_mfma_f32_16x16x32_bf16 v[112:115], v[156:159], v[180:183], v[112:115]
	v_mfma_f32_16x16x32_bf16 v[100:103], v[148:151], v[198:201], v[100:103]
	v_mfma_f32_16x16x32_bf16 v[96:99], v[156:159], v[198:201], v[96:99]
	v_mfma_f32_16x16x32_bf16 v[84:87], v[148:151], v[206:209], v[84:87]
	v_mfma_f32_16x16x32_bf16 v[80:83], v[156:159], v[206:209], v[80:83]
	v_mfma_f32_16x16x32_bf16 v[68:71], v[148:151], v[214:217], v[68:71]
	v_mfma_f32_16x16x32_bf16 v[64:67], v[156:159], v[214:217], v[64:67]
	s_barrier
	s_add_u32 s98, s44, 0x80
	s_addc_u32 s99, s45, 0
	s_add_u32 s100, s46, 0xfff80080
	s_addc_u32 s101, s47, -1
	s_add_i32 s35, s35, s6
	s_mov_b32 m0, s35
	ds_read_b128 v[176:179], v195 offset:49152
	ds_read_b128 v[180:183], v195 offset:50176
	ds_read_b128 v[184:187], v195 offset:51200
	ds_read_b128 v[198:201], v195 offset:52224
	ds_read_b128 v[202:205], v195 offset:53248
	ds_read_b128 v[206:209], v195 offset:54272
	ds_read_b128 v[210:213], v195 offset:55296
	ds_read_b128 v[214:217], v195 offset:56320
	global_load_lds_dwordx4 v162, s[98:99]
	s_add_i32 m0, s35, 0x2000
	s_add_u32 s44, s44, 0x20080
	s_addc_u32 s45, s45, 0
	s_add_i32 s35, s39, s6
	global_load_lds_dwordx4 v166, s[98:99]
	s_mov_b32 m0, s35
	s_nop 0
	global_load_lds_dwordx4 v162, s[44:45]
	s_add_i32 m0, s35, 0x2000
	s_nop 0
	global_load_lds_dwordx4 v166, s[44:45]
	s_mov_b32 m0, s28
	s_nop 0
	global_load_lds_dwordx4 v160, s[100:101]
	s_mov_b32 m0, s29
	s_nop 0
	global_load_lds_dwordx4 v164, s[100:101]
	s_waitcnt vmcnt(8)
	s_waitcnt lgkmcnt(0)
	s_barrier
	s_waitcnt lgkmcnt(0)
	v_mfma_f32_16x16x32_bf16 v[60:63], v[128:131], v[176:179], v[60:63]
	v_mfma_f32_16x16x32_bf16 v[56:59], v[136:139], v[176:179], v[56:59]
	v_mfma_f32_16x16x32_bf16 v[44:47], v[128:131], v[184:187], v[44:47]
	v_mfma_f32_16x16x32_bf16 v[40:43], v[136:139], v[184:187], v[40:43]
	v_mfma_f32_16x16x32_bf16 v[28:31], v[128:131], v[202:205], v[28:31]
	v_mfma_f32_16x16x32_bf16 v[24:27], v[136:139], v[202:205], v[24:27]
	v_mfma_f32_16x16x32_bf16 v[12:15], v[128:131], v[210:213], v[12:15]
	v_mfma_f32_16x16x32_bf16 v[8:11], v[136:139], v[210:213], v[8:11]
	v_mfma_f32_16x16x32_bf16 v[60:63], v[132:135], v[180:183], v[60:63]
	v_mfma_f32_16x16x32_bf16 v[56:59], v[140:143], v[180:183], v[56:59]
	v_mfma_f32_16x16x32_bf16 v[44:47], v[132:135], v[198:201], v[44:47]
	v_mfma_f32_16x16x32_bf16 v[40:43], v[140:143], v[198:201], v[40:43]
	v_mfma_f32_16x16x32_bf16 v[28:31], v[132:135], v[206:209], v[28:31]
	v_mfma_f32_16x16x32_bf16 v[24:27], v[140:143], v[206:209], v[24:27]
	v_mfma_f32_16x16x32_bf16 v[12:15], v[132:135], v[214:217], v[12:15]
	v_mfma_f32_16x16x32_bf16 v[8:11], v[140:143], v[214:217], v[8:11]
	v_mfma_f32_16x16x32_bf16 v[52:55], v[144:147], v[176:179], v[52:55]
	v_mfma_f32_16x16x32_bf16 v[48:51], v[152:155], v[176:179], v[48:51]
	v_mfma_f32_16x16x32_bf16 v[36:39], v[144:147], v[184:187], v[36:39]
	v_mfma_f32_16x16x32_bf16 v[32:35], v[152:155], v[184:187], v[32:35]
	v_mfma_f32_16x16x32_bf16 v[20:23], v[144:147], v[202:205], v[20:23]
	v_mfma_f32_16x16x32_bf16 v[16:19], v[152:155], v[202:205], v[16:19]
	v_mfma_f32_16x16x32_bf16 v[4:7], v[144:147], v[210:213], v[4:7]
	v_mfma_f32_16x16x32_bf16 v[0:3], v[152:155], v[210:213], v[0:3]
	v_mfma_f32_16x16x32_bf16 v[52:55], v[148:151], v[180:183], v[52:55]
	v_mfma_f32_16x16x32_bf16 v[48:51], v[156:159], v[180:183], v[48:51]
	v_mfma_f32_16x16x32_bf16 v[36:39], v[148:151], v[198:201], v[36:39]
	v_mfma_f32_16x16x32_bf16 v[32:35], v[156:159], v[198:201], v[32:35]
	v_mfma_f32_16x16x32_bf16 v[20:23], v[148:151], v[206:209], v[20:23]
	v_mfma_f32_16x16x32_bf16 v[16:19], v[156:159], v[206:209], v[16:19]
	v_mfma_f32_16x16x32_bf16 v[4:7], v[148:151], v[214:217], v[4:7]
	v_mfma_f32_16x16x32_bf16 v[0:3], v[156:159], v[214:217], v[0:3]
	s_barrier
	s_add_i32 s31, s31, 2
	s_add_u32 s42, s42, 0x100
	s_addc_u32 s43, s43, 0
	s_add_u32 s11, s11, 0x100
	s_addc_u32 s23, s23, 0
	s_cmp_gt_u32 s31, 5
	s_cbranch_scc0 .LBB0_577
	s_and_b64 vcc, exec, s[18:19]
	s_cbranch_vccz .LBB0_580
	s_barrier

.LBB0_664:
	ds_read_b128 v[156:159], v151
	ds_read_b128 v[160:163], v151 offset:1024
	ds_read_b128 v[164:167], v151 offset:2048
	ds_read_b128 v[168:171], v151 offset:3072
	ds_read_b128 v[172:175], v152
	ds_read_b128 v[176:179], v152 offset:1024
	ds_read_b128 v[180:183], v152 offset:2048
	ds_read_b128 v[184:187], v152 offset:3072
	s_add_u32 s22, s20, 0xfff80080
	s_addc_u32 s23, s21, -1
	s_cmp_eq_u32 s48, 28
	s_cselect_b32 s31, s13, s23
	s_cselect_b32 s30, s44, s22
	s_cselect_b32 s23, s15, s47
	s_cselect_b32 s22, s45, s46
	s_add_i32 m0, s11, 0xc000
	ds_read_b128 v[190:193], v153
	ds_read_b128 v[194:197], v153 offset:1024
	ds_read_b128 v[198:201], v153 offset:2048
	ds_read_b128 v[202:205], v153 offset:3072
	ds_read_b128 v[206:209], v153 offset:4096
	ds_read_b128 v[210:213], v153 offset:5120
	ds_read_b128 v[214:217], v153 offset:6144
	ds_read_b128 v[218:221], v153 offset:7168
	global_load_lds_dwordx4 v138, s[20:21]
	s_add_i32 m0, s11, 0xe000
	s_nop 0
	global_load_lds_dwordx4 v140, s[20:21]
	s_waitcnt vmcnt(8)
	s_waitcnt lgkmcnt(0)
	s_barrier
	s_waitcnt lgkmcnt(0)
	v_mfma_f32_16x16x32_bf16 v[116:119], v[156:159], v[190:193], v[116:119]
	v_mfma_f32_16x16x32_bf16 v[112:115], v[164:167], v[190:193], v[112:115]
	v_mfma_f32_16x16x32_bf16 v[100:103], v[156:159], v[198:201], v[100:103]
	v_mfma_f32_16x16x32_bf16 v[96:99], v[164:167], v[198:201], v[96:99]
	v_mfma_f32_16x16x32_bf16 v[84:87], v[156:159], v[206:209], v[84:87]
	v_mfma_f32_16x16x32_bf16 v[80:83], v[164:167], v[206:209], v[80:83]
	v_mfma_f32_16x16x32_bf16 v[68:71], v[156:159], v[214:217], v[68:71]
	v_mfma_f32_16x16x32_bf16 v[64:67], v[164:167], v[214:217], v[64:67]
	v_mfma_f32_16x16x32_bf16 v[116:119], v[160:163], v[194:197], v[116:119]
	v_mfma_f32_16x16x32_bf16 v[112:115], v[168:171], v[194:197], v[112:115]
	v_mfma_f32_16x16x32_bf16 v[100:103], v[160:163], v[202:205], v[100:103]
	v_mfma_f32_16x16x32_bf16 v[96:99], v[168:171], v[202:205], v[96:99]
	v_mfma_f32_16x16x32_bf16 v[84:87], v[160:163], v[210:213], v[84:87]
	v_mfma_f32_16x16x32_bf16 v[80:83], v[168:171], v[210:213], v[80:83]
	v_mfma_f32_16x16x32_bf16 v[68:71], v[160:163], v[218:221], v[68:71]
	v_mfma_f32_16x16x32_bf16 v[64:67], v[168:171], v[218:221], v[64:67]
	v_mfma_f32_16x16x32_bf16 v[124:127], v[172:175], v[190:193], v[124:127]
	v_mfma_f32_16x16x32_bf16 v[120:123], v[180:183], v[190:193], v[120:123]
	v_mfma_f32_16x16x32_bf16 v[108:111], v[172:175], v[198:201], v[108:111]
	v_mfma_f32_16x16x32_bf16 v[104:107], v[180:183], v[198:201], v[104:107]
	v_mfma_f32_16x16x32_bf16 v[92:95], v[172:175], v[206:209], v[92:95]
	v_mfma_f32_16x16x32_bf16 v[88:91], v[180:183], v[206:209], v[88:91]
	v_mfma_f32_16x16x32_bf16 v[76:79], v[172:175], v[214:217], v[76:79]
	v_mfma_f32_16x16x32_bf16 v[72:75], v[180:183], v[214:217], v[72:75]
	v_mfma_f32_16x16x32_bf16 v[124:127], v[176:179], v[194:197], v[124:127]
	v_mfma_f32_16x16x32_bf16 v[120:123], v[184:187], v[194:197], v[120:123]
	v_mfma_f32_16x16x32_bf16 v[108:111], v[176:179], v[202:205], v[108:111]
	v_mfma_f32_16x16x32_bf16 v[104:107], v[184:187], v[202:205], v[104:107]
	v_mfma_f32_16x16x32_bf16 v[92:95], v[176:179], v[210:213], v[92:95]
	v_mfma_f32_16x16x32_bf16 v[88:91], v[184:187], v[210:213], v[88:91]
	v_mfma_f32_16x16x32_bf16 v[76:79], v[176:179], v[218:221], v[76:79]
	v_mfma_f32_16x16x32_bf16 v[72:75], v[184:187], v[218:221], v[72:75]
	s_barrier
	s_add_i32 s49, s40, s26
	s_mov_b32 m0, s49
	ds_read_b128 v[190:193], v153 offset:16384
	ds_read_b128 v[194:197], v153 offset:17408
	ds_read_b128 v[198:201], v153 offset:18432
	ds_read_b128 v[202:205], v153 offset:19456
	ds_read_b128 v[206:209], v153 offset:20480
	ds_read_b128 v[210:213], v153 offset:21504
	ds_read_b128 v[214:217], v153 offset:22528
	ds_read_b128 v[218:221], v153 offset:23552
	global_load_lds_dwordx4 v130, s[22:23]
	s_add_i32 m0, s49, 0x2000
	s_add_u32 s50, s22, 0x80000
	s_addc_u32 s51, s23, 0
	s_add_i32 s49, s41, s26
	global_load_lds_dwordx4 v134, s[22:23]
	s_mov_b32 m0, s49
	s_nop 0
	global_load_lds_dwordx4 v130, s[50:51]
	s_add_i32 m0, s49, 0x2000
	s_nop 0
	global_load_lds_dwordx4 v134, s[50:51]
	s_mov_b32 m0, s11
	s_nop 0
	global_load_lds_dwordx4 v128, s[30:31]
	s_mov_b32 m0, s28
	s_nop 0
	global_load_lds_dwordx4 v132, s[30:31]
	s_waitcnt vmcnt(8)
	s_waitcnt lgkmcnt(0)
	s_barrier
	s_waitcnt lgkmcnt(0)
	v_mfma_f32_16x16x32_bf16 v[52:55], v[156:159], v[190:193], v[52:55]
	v_mfma_f32_16x16x32_bf16 v[48:51], v[164:167], v[190:193], v[48:51]
	v_mfma_f32_16x16x32_bf16 v[36:39], v[156:159], v[198:201], v[36:39]
	v_mfma_f32_16x16x32_bf16 v[32:35], v[164:167], v[198:201], v[32:35]
	v_mfma_f32_16x16x32_bf16 v[20:23], v[156:159], v[206:209], v[20:23]
	v_mfma_f32_16x16x32_bf16 v[16:19], v[164:167], v[206:209], v[16:19]
	v_mfma_f32_16x16x32_bf16 v[8:11], v[156:159], v[214:217], v[8:11]
	v_mfma_f32_16x16x32_bf16 v[0:3], v[164:167], v[214:217], v[0:3]
	v_mfma_f32_16x16x32_bf16 v[52:55], v[160:163], v[194:197], v[52:55]
	v_mfma_f32_16x16x32_bf16 v[48:51], v[168:171], v[194:197], v[48:51]
	v_mfma_f32_16x16x32_bf16 v[36:39], v[160:163], v[202:205], v[36:39]
	v_mfma_f32_16x16x32_bf16 v[32:35], v[168:171], v[202:205], v[32:35]
	v_mfma_f32_16x16x32_bf16 v[20:23], v[160:163], v[210:213], v[20:23]
	v_mfma_f32_16x16x32_bf16 v[16:19], v[168:171], v[210:213], v[16:19]
	v_mfma_f32_16x16x32_bf16 v[8:11], v[160:163], v[218:221], v[8:11]
	v_mfma_f32_16x16x32_bf16 v[0:3], v[168:171], v[218:221], v[0:3]
	v_mfma_f32_16x16x32_bf16 v[60:63], v[172:175], v[190:193], v[60:63]
	v_mfma_f32_16x16x32_bf16 v[56:59], v[180:183], v[190:193], v[56:59]
	v_mfma_f32_16x16x32_bf16 v[44:47], v[172:175], v[198:201], v[44:47]
	v_mfma_f32_16x16x32_bf16 v[40:43], v[180:183], v[198:201], v[40:43]
	v_mfma_f32_16x16x32_bf16 v[28:31], v[172:175], v[206:209], v[28:31]
	v_mfma_f32_16x16x32_bf16 v[24:27], v[180:183], v[206:209], v[24:27]
	v_mfma_f32_16x16x32_bf16 v[12:15], v[172:175], v[214:217], v[12:15]
	v_mfma_f32_16x16x32_bf16 v[4:7], v[180:183], v[214:217], v[4:7]
	v_mfma_f32_16x16x32_bf16 v[60:63], v[176:179], v[194:197], v[60:63]
	v_mfma_f32_16x16x32_bf16 v[56:59], v[184:187], v[194:197], v[56:59]
	v_mfma_f32_16x16x32_bf16 v[44:47], v[176:179], v[202:205], v[44:47]
	v_mfma_f32_16x16x32_bf16 v[40:43], v[184:187], v[202:205], v[40:43]
	v_mfma_f32_16x16x32_bf16 v[28:31], v[176:179], v[210:213], v[28:31]
	v_mfma_f32_16x16x32_bf16 v[24:27], v[184:187], v[210:213], v[24:27]
	v_mfma_f32_16x16x32_bf16 v[12:15], v[176:179], v[218:221], v[12:15]
	v_mfma_f32_16x16x32_bf16 v[4:7], v[184:187], v[218:221], v[4:7]
	s_barrier
	s_add_i32 s49, 0, 0x18000
	s_add_i32 s50, 0, 0x1c000
	v_add_u32_e32 v168, s49, v149
	v_add_u32_e32 v184, s50, v149
	ds_read_b128 v[156:159], v168
	ds_read_b128 v[160:163], v168 offset:1024
	ds_read_b128 v[164:167], v168 offset:2048
	ds_read_b128 v[168:171], v168 offset:3072
	ds_read_b128 v[172:175], v184
	ds_read_b128 v[176:179], v184 offset:1024
	ds_read_b128 v[180:183], v184 offset:2048
	ds_read_b128 v[184:187], v184 offset:3072
	s_add_u32 s30, s30, 0x80000
	s_addc_u32 s31, s31, 0
	s_mov_b32 m0, s29
	ds_read_b128 v[190:193], v153 offset:32768
	ds_read_b128 v[194:197], v153 offset:33792
	ds_read_b128 v[198:201], v153 offset:34816
	ds_read_b128 v[202:205], v153 offset:35840
	ds_read_b128 v[206:209], v153 offset:36864
	ds_read_b128 v[210:213], v153 offset:37888
	ds_read_b128 v[214:217], v153 offset:38912
	ds_read_b128 v[218:221], v153 offset:39936
	global_load_lds_dwordx4 v128, s[30:31]
	s_mov_b32 m0, s33
	s_nop 0
	global_load_lds_dwordx4 v132, s[30:31]
	s_waitcnt vmcnt(8)
	s_waitcnt lgkmcnt(0)
	s_barrier
	s_waitcnt lgkmcnt(0)
	v_mfma_f32_16x16x32_bf16 v[116:119], v[156:159], v[190:193], v[116:119]
	v_mfma_f32_16x16x32_bf16 v[112:115], v[164:167], v[190:193], v[112:115]
	v_mfma_f32_16x16x32_bf16 v[100:103], v[156:159], v[198:201], v[100:103]
	v_mfma_f32_16x16x32_bf16 v[96:99], v[164:167], v[198:201], v[96:99]
	v_mfma_f32_16x16x32_bf16 v[84:87], v[156:159], v[206:209], v[84:87]
	v_mfma_f32_16x16x32_bf16 v[80:83], v[164:167], v[206:209], v[80:83]
	v_mfma_f32_16x16x32_bf16 v[68:71], v[156:159], v[214:217], v[68:71]
	v_mfma_f32_16x16x32_bf16 v[64:67], v[164:167], v[214:217], v[64:67]
	v_mfma_f32_16x16x32_bf16 v[116:119], v[160:163], v[194:197], v[116:119]
	v_mfma_f32_16x16x32_bf16 v[112:115], v[168:171], v[194:197], v[112:115]
	v_mfma_f32_16x16x32_bf16 v[100:103], v[160:163], v[202:205], v[100:103]
	v_mfma_f32_16x16x32_bf16 v[96:99], v[168:171], v[202:205], v[96:99]
	v_mfma_f32_16x16x32_bf16 v[84:87], v[160:163], v[210:213], v[84:87]
	v_mfma_f32_16x16x32_bf16 v[80:83], v[168:171], v[210:213], v[80:83]
	v_mfma_f32_16x16x32_bf16 v[68:71], v[160:163], v[218:221], v[68:71]
	v_mfma_f32_16x16x32_bf16 v[64:67], v[168:171], v[218:221], v[64:67]
	v_mfma_f32_16x16x32_bf16 v[124:127], v[172:175], v[190:193], v[124:127]
	v_mfma_f32_16x16x32_bf16 v[120:123], v[180:183], v[190:193], v[120:123]
	v_mfma_f32_16x16x32_bf16 v[108:111], v[172:175], v[198:201], v[108:111]
	v_mfma_f32_16x16x32_bf16 v[104:107], v[180:183], v[198:201], v[104:107]
	v_mfma_f32_16x16x32_bf16 v[92:95], v[172:175], v[206:209], v[92:95]
	v_mfma_f32_16x16x32_bf16 v[88:91], v[180:183], v[206:209], v[88:91]
	v_mfma_f32_16x16x32_bf16 v[76:79], v[172:175], v[214:217], v[76:79]
	v_mfma_f32_16x16x32_bf16 v[72:75], v[180:183], v[214:217], v[72:75]
	v_mfma_f32_16x16x32_bf16 v[124:127], v[176:179], v[194:197], v[124:127]
	v_mfma_f32_16x16x32_bf16 v[120:123], v[184:187], v[194:197], v[120:123]
	v_mfma_f32_16x16x32_bf16 v[108:111], v[176:179], v[202:205], v[108:111]
	v_mfma_f32_16x16x32_bf16 v[104:107], v[184:187], v[202:205], v[104:107]
	v_mfma_f32_16x16x32_bf16 v[92:95], v[176:179], v[210:213], v[92:95]
	v_mfma_f32_16x16x32_bf16 v[88:91], v[184:187], v[210:213], v[88:91]
	v_mfma_f32_16x16x32_bf16 v[76:79], v[176:179], v[218:221], v[76:79]
	v_mfma_f32_16x16x32_bf16 v[72:75], v[184:187], v[218:221], v[72:75]
	s_barrier
	s_add_u32 s98, s22, 0x80
	s_addc_u32 s99, s23, 0
	s_add_u32 s100, s30, 0xfff80080
	s_addc_u32 s101, s31, -1
	s_add_i32 s30, s49, s26
	s_mov_b32 m0, s30
	ds_read_b128 v[190:193], v153 offset:49152
	ds_read_b128 v[194:197], v153 offset:50176
	ds_read_b128 v[198:201], v153 offset:51200
	ds_read_b128 v[202:205], v153 offset:52224
	ds_read_b128 v[206:209], v153 offset:53248
	ds_read_b128 v[210:213], v153 offset:54272
	ds_read_b128 v[214:217], v153 offset:55296
	ds_read_b128 v[218:221], v153 offset:56320
	global_load_lds_dwordx4 v130, s[98:99]
	s_add_i32 m0, s30, 0x2000
	s_add_u32 s22, s22, 0x80080
	s_addc_u32 s23, s23, 0
	s_add_i32 s30, s50, s26
	global_load_lds_dwordx4 v134, s[98:99]
	s_mov_b32 m0, s30
	s_nop 0
	global_load_lds_dwordx4 v130, s[22:23]
	s_add_i32 m0, s30, 0x2000
	s_nop 0
	global_load_lds_dwordx4 v134, s[22:23]
	s_mov_b32 m0, s37
	s_nop 0
	global_load_lds_dwordx4 v128, s[100:101]
	s_mov_b32 m0, s38
	s_nop 0
	global_load_lds_dwordx4 v132, s[100:101]
	s_waitcnt vmcnt(8)
	s_waitcnt lgkmcnt(0)
	s_barrier
	s_waitcnt lgkmcnt(0)
	v_mfma_f32_16x16x32_bf16 v[52:55], v[156:159], v[190:193], v[52:55]
	v_mfma_f32_16x16x32_bf16 v[48:51], v[164:167], v[190:193], v[48:51]
	v_mfma_f32_16x16x32_bf16 v[36:39], v[156:159], v[198:201], v[36:39]
	v_mfma_f32_16x16x32_bf16 v[32:35], v[164:167], v[198:201], v[32:35]
	v_mfma_f32_16x16x32_bf16 v[20:23], v[156:159], v[206:209], v[20:23]
	v_mfma_f32_16x16x32_bf16 v[16:19], v[164:167], v[206:209], v[16:19]
	v_mfma_f32_16x16x32_bf16 v[8:11], v[156:159], v[214:217], v[8:11]
	v_mfma_f32_16x16x32_bf16 v[0:3], v[164:167], v[214:217], v[0:3]
	v_mfma_f32_16x16x32_bf16 v[52:55], v[160:163], v[194:197], v[52:55]
	v_mfma_f32_16x16x32_bf16 v[48:51], v[168:171], v[194:197], v[48:51]
	v_mfma_f32_16x16x32_bf16 v[36:39], v[160:163], v[202:205], v[36:39]
	v_mfma_f32_16x16x32_bf16 v[32:35], v[168:171], v[202:205], v[32:35]
	v_mfma_f32_16x16x32_bf16 v[20:23], v[160:163], v[210:213], v[20:23]
	v_mfma_f32_16x16x32_bf16 v[16:19], v[168:171], v[210:213], v[16:19]
	v_mfma_f32_16x16x32_bf16 v[8:11], v[160:163], v[218:221], v[8:11]
	v_mfma_f32_16x16x32_bf16 v[0:3], v[168:171], v[218:221], v[0:3]
	v_mfma_f32_16x16x32_bf16 v[60:63], v[172:175], v[190:193], v[60:63]
	v_mfma_f32_16x16x32_bf16 v[56:59], v[180:183], v[190:193], v[56:59]
	v_mfma_f32_16x16x32_bf16 v[44:47], v[172:175], v[198:201], v[44:47]
	v_mfma_f32_16x16x32_bf16 v[40:43], v[180:183], v[198:201], v[40:43]
	v_mfma_f32_16x16x32_bf16 v[28:31], v[172:175], v[206:209], v[28:31]
	v_mfma_f32_16x16x32_bf16 v[24:27], v[180:183], v[206:209], v[24:27]
	v_mfma_f32_16x16x32_bf16 v[12:15], v[172:175], v[214:217], v[12:15]
	v_mfma_f32_16x16x32_bf16 v[4:7], v[180:183], v[214:217], v[4:7]
	v_mfma_f32_16x16x32_bf16 v[60:63], v[176:179], v[194:197], v[60:63]
	v_mfma_f32_16x16x32_bf16 v[56:59], v[184:187], v[194:197], v[56:59]
	v_mfma_f32_16x16x32_bf16 v[44:47], v[176:179], v[202:205], v[44:47]
	v_mfma_f32_16x16x32_bf16 v[40:43], v[184:187], v[202:205], v[40:43]
	v_mfma_f32_16x16x32_bf16 v[28:31], v[176:179], v[210:213], v[28:31]
	v_mfma_f32_16x16x32_bf16 v[24:27], v[184:187], v[210:213], v[24:27]
	v_mfma_f32_16x16x32_bf16 v[12:15], v[176:179], v[218:221], v[12:15]
	v_mfma_f32_16x16x32_bf16 v[4:7], v[184:187], v[218:221], v[4:7]
	s_barrier
	s_add_i32 s48, s48, 2
	s_add_u32 s20, s20, 0x100
	s_addc_u32 s21, s21, 0
	s_add_u32 s46, s46, 0x100
	s_addc_u32 s47, s47, 0
	s_cmp_gt_u32 s48, 29
	s_cbranch_scc0 .LBB0_664
	s_and_b64 vcc, exec, s[8:9]
	s_cbranch_vccz .LBB0_667
	s_barrier

.LBB0_749:
	ds_read_b128 v[128:131], v179
	ds_read_b128 v[132:135], v179 offset:1024
	ds_read_b128 v[136:139], v179 offset:2048
	ds_read_b128 v[140:143], v179 offset:3072
	ds_read_b128 v[160:163], v180
	ds_read_b128 v[164:167], v180 offset:1024
	ds_read_b128 v[168:171], v180 offset:2048
	ds_read_b128 v[172:175], v180 offset:3072
	s_add_u32 s20, s10, 0xffea0080
	s_addc_u32 s21, s11, -1
	s_cmpk_eq_i32 s48, 0x54
	s_cselect_b32 s23, s1, s21
	s_cselect_b32 s22, s0, s20
	s_cselect_b32 s21, s19, s47
	s_cselect_b32 s20, s18, s46
	s_add_i32 m0, s27, 0xc000
	ds_read_b128 v[184:187], v181
	ds_read_b128 v[190:193], v181 offset:1024
	ds_read_b128 v[194:197], v181 offset:2048
	ds_read_b128 v[198:201], v181 offset:3072
	ds_read_b128 v[202:205], v181 offset:4096
	ds_read_b128 v[206:209], v181 offset:5120
	ds_read_b128 v[210:213], v181 offset:6144
	ds_read_b128 v[214:217], v181 offset:7168
	global_load_lds_dwordx4 v152, s[10:11]
	s_add_i32 m0, s27, 0xe000
	s_nop 0
	global_load_lds_dwordx4 v154, s[10:11]
	s_waitcnt vmcnt(8)
	s_waitcnt lgkmcnt(0)
	s_barrier
	s_waitcnt lgkmcnt(0)
	v_mfma_f32_16x16x32_bf16 v[124:127], v[128:131], v[184:187], v[124:127]
	v_mfma_f32_16x16x32_bf16 v[120:123], v[136:139], v[184:187], v[120:123]
	v_mfma_f32_16x16x32_bf16 v[108:111], v[128:131], v[194:197], v[108:111]
	v_mfma_f32_16x16x32_bf16 v[104:107], v[136:139], v[194:197], v[104:107]
	v_mfma_f32_16x16x32_bf16 v[92:95], v[128:131], v[202:205], v[92:95]
	v_mfma_f32_16x16x32_bf16 v[88:91], v[136:139], v[202:205], v[88:91]
	v_mfma_f32_16x16x32_bf16 v[76:79], v[128:131], v[210:213], v[76:79]
	v_mfma_f32_16x16x32_bf16 v[72:75], v[136:139], v[210:213], v[72:75]
	v_mfma_f32_16x16x32_bf16 v[124:127], v[132:135], v[190:193], v[124:127]
	v_mfma_f32_16x16x32_bf16 v[120:123], v[140:143], v[190:193], v[120:123]
	v_mfma_f32_16x16x32_bf16 v[108:111], v[132:135], v[198:201], v[108:111]
	v_mfma_f32_16x16x32_bf16 v[104:107], v[140:143], v[198:201], v[104:107]
	v_mfma_f32_16x16x32_bf16 v[92:95], v[132:135], v[206:209], v[92:95]
	v_mfma_f32_16x16x32_bf16 v[88:91], v[140:143], v[206:209], v[88:91]
	v_mfma_f32_16x16x32_bf16 v[76:79], v[132:135], v[214:217], v[76:79]
	v_mfma_f32_16x16x32_bf16 v[72:75], v[140:143], v[214:217], v[72:75]
	v_mfma_f32_16x16x32_bf16 v[116:119], v[160:163], v[184:187], v[116:119]
	v_mfma_f32_16x16x32_bf16 v[112:115], v[168:171], v[184:187], v[112:115]
	v_mfma_f32_16x16x32_bf16 v[100:103], v[160:163], v[194:197], v[100:103]
	v_mfma_f32_16x16x32_bf16 v[96:99], v[168:171], v[194:197], v[96:99]
	v_mfma_f32_16x16x32_bf16 v[84:87], v[160:163], v[202:205], v[84:87]
	v_mfma_f32_16x16x32_bf16 v[80:83], v[168:171], v[202:205], v[80:83]
	v_mfma_f32_16x16x32_bf16 v[68:71], v[160:163], v[210:213], v[68:71]
	v_mfma_f32_16x16x32_bf16 v[64:67], v[168:171], v[210:213], v[64:67]
	v_mfma_f32_16x16x32_bf16 v[116:119], v[164:167], v[190:193], v[116:119]
	v_mfma_f32_16x16x32_bf16 v[112:115], v[172:175], v[190:193], v[112:115]
	v_mfma_f32_16x16x32_bf16 v[100:103], v[164:167], v[198:201], v[100:103]
	v_mfma_f32_16x16x32_bf16 v[96:99], v[172:175], v[198:201], v[96:99]
	v_mfma_f32_16x16x32_bf16 v[84:87], v[164:167], v[206:209], v[84:87]
	v_mfma_f32_16x16x32_bf16 v[80:83], v[172:175], v[206:209], v[80:83]
	v_mfma_f32_16x16x32_bf16 v[68:71], v[164:167], v[214:217], v[68:71]
	v_mfma_f32_16x16x32_bf16 v[64:67], v[172:175], v[214:217], v[64:67]
	s_barrier
	s_add_i32 s49, s39, s26
	s_mov_b32 m0, s49
	ds_read_b128 v[184:187], v181 offset:16384
	ds_read_b128 v[190:193], v181 offset:17408
	ds_read_b128 v[194:197], v181 offset:18432
	ds_read_b128 v[198:201], v181 offset:19456
	ds_read_b128 v[202:205], v181 offset:20480
	ds_read_b128 v[206:209], v181 offset:21504
	ds_read_b128 v[210:213], v181 offset:22528
	ds_read_b128 v[214:217], v181 offset:23552
	global_load_lds_dwordx4 v146, s[20:21]
	s_add_i32 m0, s49, 0x2000
	s_add_u32 s50, s20, 0x160000
	s_addc_u32 s51, s21, 0
	s_add_i32 s49, s40, s26
	global_load_lds_dwordx4 v150, s[20:21]
	s_mov_b32 m0, s49
	s_nop 0
	global_load_lds_dwordx4 v146, s[50:51]
	s_add_i32 m0, s49, 0x2000
	s_nop 0
	global_load_lds_dwordx4 v150, s[50:51]
	s_mov_b32 m0, s27
	s_nop 0
	global_load_lds_dwordx4 v144, s[22:23]
	s_mov_b32 m0, s28
	s_nop 0
	global_load_lds_dwordx4 v148, s[22:23]
	s_waitcnt vmcnt(8)
	s_waitcnt lgkmcnt(0)
	s_barrier
	s_waitcnt lgkmcnt(0)
	v_mfma_f32_16x16x32_bf16 v[60:63], v[128:131], v[184:187], v[60:63]
	v_mfma_f32_16x16x32_bf16 v[56:59], v[136:139], v[184:187], v[56:59]
	v_mfma_f32_16x16x32_bf16 v[44:47], v[128:131], v[194:197], v[44:47]
	v_mfma_f32_16x16x32_bf16 v[40:43], v[136:139], v[194:197], v[40:43]
	v_mfma_f32_16x16x32_bf16 v[28:31], v[128:131], v[202:205], v[28:31]
	v_mfma_f32_16x16x32_bf16 v[24:27], v[136:139], v[202:205], v[24:27]
	v_mfma_f32_16x16x32_bf16 v[12:15], v[128:131], v[210:213], v[12:15]
	v_mfma_f32_16x16x32_bf16 v[8:11], v[136:139], v[210:213], v[8:11]
	v_mfma_f32_16x16x32_bf16 v[60:63], v[132:135], v[190:193], v[60:63]
	v_mfma_f32_16x16x32_bf16 v[56:59], v[140:143], v[190:193], v[56:59]
	v_mfma_f32_16x16x32_bf16 v[44:47], v[132:135], v[198:201], v[44:47]
	v_mfma_f32_16x16x32_bf16 v[40:43], v[140:143], v[198:201], v[40:43]
	v_mfma_f32_16x16x32_bf16 v[28:31], v[132:135], v[206:209], v[28:31]
	v_mfma_f32_16x16x32_bf16 v[24:27], v[140:143], v[206:209], v[24:27]
	v_mfma_f32_16x16x32_bf16 v[12:15], v[132:135], v[214:217], v[12:15]
	v_mfma_f32_16x16x32_bf16 v[8:11], v[140:143], v[214:217], v[8:11]
	v_mfma_f32_16x16x32_bf16 v[52:55], v[160:163], v[184:187], v[52:55]
	v_mfma_f32_16x16x32_bf16 v[48:51], v[168:171], v[184:187], v[48:51]
	v_mfma_f32_16x16x32_bf16 v[36:39], v[160:163], v[194:197], v[36:39]
	v_mfma_f32_16x16x32_bf16 v[32:35], v[168:171], v[194:197], v[32:35]
	v_mfma_f32_16x16x32_bf16 v[20:23], v[160:163], v[202:205], v[20:23]
	v_mfma_f32_16x16x32_bf16 v[16:19], v[168:171], v[202:205], v[16:19]
	v_mfma_f32_16x16x32_bf16 v[4:7], v[160:163], v[210:213], v[4:7]
	v_mfma_f32_16x16x32_bf16 v[0:3], v[168:171], v[210:213], v[0:3]
	v_mfma_f32_16x16x32_bf16 v[52:55], v[164:167], v[190:193], v[52:55]
	v_mfma_f32_16x16x32_bf16 v[48:51], v[172:175], v[190:193], v[48:51]
	v_mfma_f32_16x16x32_bf16 v[36:39], v[164:167], v[198:201], v[36:39]
	v_mfma_f32_16x16x32_bf16 v[32:35], v[172:175], v[198:201], v[32:35]
	v_mfma_f32_16x16x32_bf16 v[20:23], v[164:167], v[206:209], v[20:23]
	v_mfma_f32_16x16x32_bf16 v[16:19], v[172:175], v[206:209], v[16:19]
	v_mfma_f32_16x16x32_bf16 v[4:7], v[164:167], v[214:217], v[4:7]
	v_mfma_f32_16x16x32_bf16 v[0:3], v[172:175], v[214:217], v[0:3]
	s_barrier
	s_add_i32 s49, 0, 0x18000
	s_add_i32 s50, 0, 0x1c000
	v_add_u32_e32 v140, s49, v177
	v_add_u32_e32 v172, s50, v177
	ds_read_b128 v[128:131], v140
	ds_read_b128 v[132:135], v140 offset:1024
	ds_read_b128 v[136:139], v140 offset:2048
	ds_read_b128 v[140:143], v140 offset:3072
	ds_read_b128 v[160:163], v172
	ds_read_b128 v[164:167], v172 offset:1024
	ds_read_b128 v[168:171], v172 offset:2048
	ds_read_b128 v[172:175], v172 offset:3072
	s_add_u32 s22, s22, 0x160000
	s_addc_u32 s23, s23, 0
	s_mov_b32 m0, s29
	ds_read_b128 v[184:187], v181 offset:32768
	ds_read_b128 v[190:193], v181 offset:33792
	ds_read_b128 v[194:197], v181 offset:34816
	ds_read_b128 v[198:201], v181 offset:35840
	ds_read_b128 v[202:205], v181 offset:36864
	ds_read_b128 v[206:209], v181 offset:37888
	ds_read_b128 v[210:213], v181 offset:38912
	ds_read_b128 v[214:217], v181 offset:39936
	global_load_lds_dwordx4 v144, s[22:23]
	s_mov_b32 m0, s30
	s_nop 0
	global_load_lds_dwordx4 v148, s[22:23]
	s_waitcnt vmcnt(8)
	s_waitcnt lgkmcnt(0)
	s_barrier
	s_waitcnt lgkmcnt(0)
	v_mfma_f32_16x16x32_bf16 v[124:127], v[128:131], v[184:187], v[124:127]
	v_mfma_f32_16x16x32_bf16 v[120:123], v[136:139], v[184:187], v[120:123]
	v_mfma_f32_16x16x32_bf16 v[108:111], v[128:131], v[194:197], v[108:111]
	v_mfma_f32_16x16x32_bf16 v[104:107], v[136:139], v[194:197], v[104:107]
	v_mfma_f32_16x16x32_bf16 v[92:95], v[128:131], v[202:205], v[92:95]
	v_mfma_f32_16x16x32_bf16 v[88:91], v[136:139], v[202:205], v[88:91]
	v_mfma_f32_16x16x32_bf16 v[76:79], v[128:131], v[210:213], v[76:79]
	v_mfma_f32_16x16x32_bf16 v[72:75], v[136:139], v[210:213], v[72:75]
	v_mfma_f32_16x16x32_bf16 v[124:127], v[132:135], v[190:193], v[124:127]
	v_mfma_f32_16x16x32_bf16 v[120:123], v[140:143], v[190:193], v[120:123]
	v_mfma_f32_16x16x32_bf16 v[108:111], v[132:135], v[198:201], v[108:111]
	v_mfma_f32_16x16x32_bf16 v[104:107], v[140:143], v[198:201], v[104:107]
	v_mfma_f32_16x16x32_bf16 v[92:95], v[132:135], v[206:209], v[92:95]
	v_mfma_f32_16x16x32_bf16 v[88:91], v[140:143], v[206:209], v[88:91]
	v_mfma_f32_16x16x32_bf16 v[76:79], v[132:135], v[214:217], v[76:79]
	v_mfma_f32_16x16x32_bf16 v[72:75], v[140:143], v[214:217], v[72:75]
	v_mfma_f32_16x16x32_bf16 v[116:119], v[160:163], v[184:187], v[116:119]
	v_mfma_f32_16x16x32_bf16 v[112:115], v[168:171], v[184:187], v[112:115]
	v_mfma_f32_16x16x32_bf16 v[100:103], v[160:163], v[194:197], v[100:103]
	v_mfma_f32_16x16x32_bf16 v[96:99], v[168:171], v[194:197], v[96:99]
	v_mfma_f32_16x16x32_bf16 v[84:87], v[160:163], v[202:205], v[84:87]
	v_mfma_f32_16x16x32_bf16 v[80:83], v[168:171], v[202:205], v[80:83]
	v_mfma_f32_16x16x32_bf16 v[68:71], v[160:163], v[210:213], v[68:71]
	v_mfma_f32_16x16x32_bf16 v[64:67], v[168:171], v[210:213], v[64:67]
	v_mfma_f32_16x16x32_bf16 v[116:119], v[164:167], v[190:193], v[116:119]
	v_mfma_f32_16x16x32_bf16 v[112:115], v[172:175], v[190:193], v[112:115]
	v_mfma_f32_16x16x32_bf16 v[100:103], v[164:167], v[198:201], v[100:103]
	v_mfma_f32_16x16x32_bf16 v[96:99], v[172:175], v[198:201], v[96:99]
	v_mfma_f32_16x16x32_bf16 v[84:87], v[164:167], v[206:209], v[84:87]
	v_mfma_f32_16x16x32_bf16 v[80:83], v[172:175], v[206:209], v[80:83]
	v_mfma_f32_16x16x32_bf16 v[68:71], v[164:167], v[214:217], v[68:71]
	v_mfma_f32_16x16x32_bf16 v[64:67], v[172:175], v[214:217], v[64:67]
	s_barrier
	s_add_u32 s98, s20, 0x80
	s_addc_u32 s99, s21, 0
	s_add_u32 s100, s22, 0xffea0080
	s_addc_u32 s101, s23, -1
	s_add_i32 s22, s49, s26
	s_mov_b32 m0, s22
	ds_read_b128 v[184:187], v181 offset:49152
	ds_read_b128 v[190:193], v181 offset:50176
	ds_read_b128 v[194:197], v181 offset:51200
	ds_read_b128 v[198:201], v181 offset:52224
	ds_read_b128 v[202:205], v181 offset:53248
	ds_read_b128 v[206:209], v181 offset:54272
	ds_read_b128 v[210:213], v181 offset:55296
	ds_read_b128 v[214:217], v181 offset:56320
	global_load_lds_dwordx4 v146, s[98:99]
	s_add_i32 m0, s22, 0x2000
	s_add_u32 s20, s20, 0x160080
	s_addc_u32 s21, s21, 0
	s_add_i32 s22, s50, s26
	global_load_lds_dwordx4 v150, s[98:99]
	s_mov_b32 m0, s22
	s_nop 0
	global_load_lds_dwordx4 v146, s[20:21]
	s_add_i32 m0, s22, 0x2000
	s_nop 0
	global_load_lds_dwordx4 v150, s[20:21]
	s_mov_b32 m0, s35
	s_nop 0
	global_load_lds_dwordx4 v144, s[100:101]
	s_mov_b32 m0, s36
	s_nop 0
	global_load_lds_dwordx4 v148, s[100:101]
	s_waitcnt vmcnt(8)
	s_waitcnt lgkmcnt(0)
	s_barrier
	s_waitcnt lgkmcnt(0)
	v_mfma_f32_16x16x32_bf16 v[60:63], v[128:131], v[184:187], v[60:63]
	v_mfma_f32_16x16x32_bf16 v[56:59], v[136:139], v[184:187], v[56:59]
	v_mfma_f32_16x16x32_bf16 v[44:47], v[128:131], v[194:197], v[44:47]
	v_mfma_f32_16x16x32_bf16 v[40:43], v[136:139], v[194:197], v[40:43]
	v_mfma_f32_16x16x32_bf16 v[28:31], v[128:131], v[202:205], v[28:31]
	v_mfma_f32_16x16x32_bf16 v[24:27], v[136:139], v[202:205], v[24:27]
	v_mfma_f32_16x16x32_bf16 v[12:15], v[128:131], v[210:213], v[12:15]
	v_mfma_f32_16x16x32_bf16 v[8:11], v[136:139], v[210:213], v[8:11]
	v_mfma_f32_16x16x32_bf16 v[60:63], v[132:135], v[190:193], v[60:63]
	v_mfma_f32_16x16x32_bf16 v[56:59], v[140:143], v[190:193], v[56:59]
	v_mfma_f32_16x16x32_bf16 v[44:47], v[132:135], v[198:201], v[44:47]
	v_mfma_f32_16x16x32_bf16 v[40:43], v[140:143], v[198:201], v[40:43]
	v_mfma_f32_16x16x32_bf16 v[28:31], v[132:135], v[206:209], v[28:31]
	v_mfma_f32_16x16x32_bf16 v[24:27], v[140:143], v[206:209], v[24:27]
	v_mfma_f32_16x16x32_bf16 v[12:15], v[132:135], v[214:217], v[12:15]
	v_mfma_f32_16x16x32_bf16 v[8:11], v[140:143], v[214:217], v[8:11]
	v_mfma_f32_16x16x32_bf16 v[52:55], v[160:163], v[184:187], v[52:55]
	v_mfma_f32_16x16x32_bf16 v[48:51], v[168:171], v[184:187], v[48:51]
	v_mfma_f32_16x16x32_bf16 v[36:39], v[160:163], v[194:197], v[36:39]
	v_mfma_f32_16x16x32_bf16 v[32:35], v[168:171], v[194:197], v[32:35]
	v_mfma_f32_16x16x32_bf16 v[20:23], v[160:163], v[202:205], v[20:23]
	v_mfma_f32_16x16x32_bf16 v[16:19], v[168:171], v[202:205], v[16:19]
	v_mfma_f32_16x16x32_bf16 v[4:7], v[160:163], v[210:213], v[4:7]
	v_mfma_f32_16x16x32_bf16 v[0:3], v[168:171], v[210:213], v[0:3]
	v_mfma_f32_16x16x32_bf16 v[52:55], v[164:167], v[190:193], v[52:55]
	v_mfma_f32_16x16x32_bf16 v[48:51], v[172:175], v[190:193], v[48:51]
	v_mfma_f32_16x16x32_bf16 v[36:39], v[164:167], v[198:201], v[36:39]
	v_mfma_f32_16x16x32_bf16 v[32:35], v[172:175], v[198:201], v[32:35]
	v_mfma_f32_16x16x32_bf16 v[20:23], v[164:167], v[206:209], v[20:23]
	v_mfma_f32_16x16x32_bf16 v[16:19], v[172:175], v[206:209], v[16:19]
	v_mfma_f32_16x16x32_bf16 v[4:7], v[164:167], v[214:217], v[4:7]
	v_mfma_f32_16x16x32_bf16 v[0:3], v[172:175], v[214:217], v[0:3]
	s_barrier
	s_add_i32 s48, s48, 2
	s_add_u32 s10, s10, 0x100
	s_addc_u32 s11, s11, 0
	s_add_u32 s46, s46, 0x100
	s_addc_u32 s47, s47, 0
	s_cmpk_gt_u32 s48, 0x55
	s_cbranch_scc0 .LBB0_749
	s_and_b64 vcc, exec, s[14:15]
	s_cbranch_vccz .LBB0_752
	s_barrier

.LBB0_838:
	ds_read_b128 v[154:157], v143
	ds_read_b128 v[164:167], v143 offset:1024
	ds_read_b128 v[168:171], v143 offset:2048
	ds_read_b128 v[172:175], v143 offset:3072
	ds_read_b128 v[176:179], v160
	ds_read_b128 v[180:183], v160 offset:1024
	ds_read_b128 v[184:187], v160 offset:2048
	ds_read_b128 v[190:193], v160 offset:3072
	s_add_u32 s44, s10, 0xfff80080
	s_addc_u32 s45, s11, -1
	s_cmp_eq_u32 s62, 28
	s_cselect_b32 s47, s7, s45
	s_cselect_b32 s46, s35, s44
	s_cselect_b32 s45, s37, s61
	s_cselect_b32 s44, s59, s60
	s_add_i32 m0, s27, 0xc000
	ds_read_b128 v[194:197], v161
	ds_read_b128 v[198:201], v161 offset:1024
	ds_read_b128 v[202:205], v161 offset:2048
	ds_read_b128 v[206:209], v161 offset:3072
	ds_read_b128 v[210:213], v161 offset:4096
	ds_read_b128 v[214:217], v161 offset:5120
	ds_read_b128 v[218:221], v161 offset:6144
	ds_read_b128 v[222:225], v161 offset:7168
	global_load_lds_dwordx4 v146, s[10:11]
	s_add_i32 m0, s27, 0xe000
	s_nop 0
	global_load_lds_dwordx4 v148, s[10:11]
	s_waitcnt vmcnt(8)
	s_waitcnt lgkmcnt(0)
	s_barrier
	s_waitcnt lgkmcnt(0)
	v_mfma_f32_16x16x32_bf16 v[124:127], v[154:157], v[194:197], v[124:127]
	v_mfma_f32_16x16x32_bf16 v[120:123], v[168:171], v[194:197], v[120:123]
	v_mfma_f32_16x16x32_bf16 v[108:111], v[154:157], v[202:205], v[108:111]
	v_mfma_f32_16x16x32_bf16 v[104:107], v[168:171], v[202:205], v[104:107]
	v_mfma_f32_16x16x32_bf16 v[92:95], v[154:157], v[210:213], v[92:95]
	v_mfma_f32_16x16x32_bf16 v[88:91], v[168:171], v[210:213], v[88:91]
	v_mfma_f32_16x16x32_bf16 v[76:79], v[154:157], v[218:221], v[76:79]
	v_mfma_f32_16x16x32_bf16 v[72:75], v[168:171], v[218:221], v[72:75]
	v_mfma_f32_16x16x32_bf16 v[124:127], v[164:167], v[198:201], v[124:127]
	v_mfma_f32_16x16x32_bf16 v[120:123], v[172:175], v[198:201], v[120:123]
	v_mfma_f32_16x16x32_bf16 v[108:111], v[164:167], v[206:209], v[108:111]
	v_mfma_f32_16x16x32_bf16 v[104:107], v[172:175], v[206:209], v[104:107]
	v_mfma_f32_16x16x32_bf16 v[92:95], v[164:167], v[214:217], v[92:95]
	v_mfma_f32_16x16x32_bf16 v[88:91], v[172:175], v[214:217], v[88:91]
	v_mfma_f32_16x16x32_bf16 v[76:79], v[164:167], v[222:225], v[76:79]
	v_mfma_f32_16x16x32_bf16 v[72:75], v[172:175], v[222:225], v[72:75]
	v_mfma_f32_16x16x32_bf16 v[116:119], v[176:179], v[194:197], v[116:119]
	v_mfma_f32_16x16x32_bf16 v[112:115], v[184:187], v[194:197], v[112:115]
	v_mfma_f32_16x16x32_bf16 v[100:103], v[176:179], v[202:205], v[100:103]
	v_mfma_f32_16x16x32_bf16 v[96:99], v[184:187], v[202:205], v[96:99]
	v_mfma_f32_16x16x32_bf16 v[84:87], v[176:179], v[210:213], v[84:87]
	v_mfma_f32_16x16x32_bf16 v[80:83], v[184:187], v[210:213], v[80:83]
	v_mfma_f32_16x16x32_bf16 v[68:71], v[176:179], v[218:221], v[68:71]
	v_mfma_f32_16x16x32_bf16 v[64:67], v[184:187], v[218:221], v[64:67]
	v_mfma_f32_16x16x32_bf16 v[116:119], v[180:183], v[198:201], v[116:119]
	v_mfma_f32_16x16x32_bf16 v[112:115], v[190:193], v[198:201], v[112:115]
	v_mfma_f32_16x16x32_bf16 v[100:103], v[180:183], v[206:209], v[100:103]
	v_mfma_f32_16x16x32_bf16 v[96:99], v[190:193], v[206:209], v[96:99]
	v_mfma_f32_16x16x32_bf16 v[84:87], v[180:183], v[214:217], v[84:87]
	v_mfma_f32_16x16x32_bf16 v[80:83], v[190:193], v[214:217], v[80:83]
	v_mfma_f32_16x16x32_bf16 v[68:71], v[180:183], v[222:225], v[68:71]
	v_mfma_f32_16x16x32_bf16 v[64:67], v[190:193], v[222:225], v[64:67]
	s_barrier
	s_add_i32 s63, s54, s26
	s_mov_b32 m0, s63
	ds_read_b128 v[194:197], v161 offset:16384
	ds_read_b128 v[198:201], v161 offset:17408
	ds_read_b128 v[202:205], v161 offset:18432
	ds_read_b128 v[206:209], v161 offset:19456
	ds_read_b128 v[210:213], v161 offset:20480
	ds_read_b128 v[214:217], v161 offset:21504
	ds_read_b128 v[218:221], v161 offset:22528
	ds_read_b128 v[222:225], v161 offset:23552
	global_load_lds_dwordx4 v130, s[44:45]
	s_add_i32 m0, s63, 0x2000
	s_add_u32 s64, s44, 0x80000
	s_addc_u32 s65, s45, 0
	s_add_i32 s63, s55, s26
	global_load_lds_dwordx4 v134, s[44:45]
	s_mov_b32 m0, s63
	s_nop 0
	global_load_lds_dwordx4 v130, s[64:65]
	s_add_i32 m0, s63, 0x2000
	s_nop 0
	global_load_lds_dwordx4 v134, s[64:65]
	s_mov_b32 m0, s27
	s_nop 0
	global_load_lds_dwordx4 v128, s[46:47]
	s_mov_b32 m0, s28
	s_nop 0
	global_load_lds_dwordx4 v132, s[46:47]
	s_waitcnt vmcnt(8)
	s_waitcnt lgkmcnt(0)
	s_barrier
	s_waitcnt lgkmcnt(0)
	v_mfma_f32_16x16x32_bf16 v[60:63], v[154:157], v[194:197], v[60:63]
	v_mfma_f32_16x16x32_bf16 v[56:59], v[168:171], v[194:197], v[56:59]
	v_mfma_f32_16x16x32_bf16 v[44:47], v[154:157], v[202:205], v[44:47]
	v_mfma_f32_16x16x32_bf16 v[40:43], v[168:171], v[202:205], v[40:43]
	v_mfma_f32_16x16x32_bf16 v[28:31], v[154:157], v[210:213], v[28:31]
	v_mfma_f32_16x16x32_bf16 v[24:27], v[168:171], v[210:213], v[24:27]
	v_mfma_f32_16x16x32_bf16 v[12:15], v[154:157], v[218:221], v[12:15]
	v_mfma_f32_16x16x32_bf16 v[8:11], v[168:171], v[218:221], v[8:11]
	v_mfma_f32_16x16x32_bf16 v[60:63], v[164:167], v[198:201], v[60:63]
	v_mfma_f32_16x16x32_bf16 v[56:59], v[172:175], v[198:201], v[56:59]
	v_mfma_f32_16x16x32_bf16 v[44:47], v[164:167], v[206:209], v[44:47]
	v_mfma_f32_16x16x32_bf16 v[40:43], v[172:175], v[206:209], v[40:43]
	v_mfma_f32_16x16x32_bf16 v[28:31], v[164:167], v[214:217], v[28:31]
	v_mfma_f32_16x16x32_bf16 v[24:27], v[172:175], v[214:217], v[24:27]
	v_mfma_f32_16x16x32_bf16 v[12:15], v[164:167], v[222:225], v[12:15]
	v_mfma_f32_16x16x32_bf16 v[8:11], v[172:175], v[222:225], v[8:11]
	v_mfma_f32_16x16x32_bf16 v[52:55], v[176:179], v[194:197], v[52:55]
	v_mfma_f32_16x16x32_bf16 v[48:51], v[184:187], v[194:197], v[48:51]
	v_mfma_f32_16x16x32_bf16 v[36:39], v[176:179], v[202:205], v[36:39]
	v_mfma_f32_16x16x32_bf16 v[32:35], v[184:187], v[202:205], v[32:35]
	v_mfma_f32_16x16x32_bf16 v[20:23], v[176:179], v[210:213], v[20:23]
	v_mfma_f32_16x16x32_bf16 v[16:19], v[184:187], v[210:213], v[16:19]
	v_mfma_f32_16x16x32_bf16 v[4:7], v[176:179], v[218:221], v[4:7]
	v_mfma_f32_16x16x32_bf16 v[0:3], v[184:187], v[218:221], v[0:3]
	v_mfma_f32_16x16x32_bf16 v[52:55], v[180:183], v[198:201], v[52:55]
	v_mfma_f32_16x16x32_bf16 v[48:51], v[190:193], v[198:201], v[48:51]
	v_mfma_f32_16x16x32_bf16 v[36:39], v[180:183], v[206:209], v[36:39]
	v_mfma_f32_16x16x32_bf16 v[32:35], v[190:193], v[206:209], v[32:35]
	v_mfma_f32_16x16x32_bf16 v[20:23], v[180:183], v[214:217], v[20:23]
	v_mfma_f32_16x16x32_bf16 v[16:19], v[190:193], v[214:217], v[16:19]
	v_mfma_f32_16x16x32_bf16 v[4:7], v[180:183], v[222:225], v[4:7]
	v_mfma_f32_16x16x32_bf16 v[0:3], v[190:193], v[222:225], v[0:3]
	s_barrier
	s_add_i32 s63, 0, 0x18000
	v_add_u32_e32 v136, s63, v159
	s_add_i32 s64, 0, 0x1c000
	ds_read_b128 v[154:157], v136
	ds_read_b128 v[164:167], v136 offset:1024
	ds_read_b128 v[168:171], v136 offset:2048
	ds_read_b128 v[172:175], v136 offset:3072
	v_add_u32_e32 v136, s64, v159
	ds_read_b128 v[176:179], v136
	ds_read_b128 v[180:183], v136 offset:1024
	ds_read_b128 v[184:187], v136 offset:2048
	ds_read_b128 v[190:193], v136 offset:3072
	s_add_u32 s46, s46, 0x80000
	s_addc_u32 s47, s47, 0
	s_mov_b32 m0, s29
	ds_read_b128 v[194:197], v161 offset:32768
	ds_read_b128 v[198:201], v161 offset:33792
	ds_read_b128 v[202:205], v161 offset:34816
	ds_read_b128 v[206:209], v161 offset:35840
	ds_read_b128 v[210:213], v161 offset:36864
	ds_read_b128 v[214:217], v161 offset:37888
	ds_read_b128 v[218:221], v161 offset:38912
	ds_read_b128 v[222:225], v161 offset:39936
	global_load_lds_dwordx4 v128, s[46:47]
	s_mov_b32 m0, s33
	s_nop 0
	global_load_lds_dwordx4 v132, s[46:47]
	s_waitcnt vmcnt(8)
	s_waitcnt lgkmcnt(0)
	s_barrier
	s_waitcnt lgkmcnt(0)
	v_mfma_f32_16x16x32_bf16 v[124:127], v[154:157], v[194:197], v[124:127]
	v_mfma_f32_16x16x32_bf16 v[120:123], v[168:171], v[194:197], v[120:123]
	v_mfma_f32_16x16x32_bf16 v[108:111], v[154:157], v[202:205], v[108:111]
	v_mfma_f32_16x16x32_bf16 v[104:107], v[168:171], v[202:205], v[104:107]
	v_mfma_f32_16x16x32_bf16 v[92:95], v[154:157], v[210:213], v[92:95]
	v_mfma_f32_16x16x32_bf16 v[88:91], v[168:171], v[210:213], v[88:91]
	v_mfma_f32_16x16x32_bf16 v[76:79], v[154:157], v[218:221], v[76:79]
	v_mfma_f32_16x16x32_bf16 v[72:75], v[168:171], v[218:221], v[72:75]
	v_mfma_f32_16x16x32_bf16 v[124:127], v[164:167], v[198:201], v[124:127]
	v_mfma_f32_16x16x32_bf16 v[120:123], v[172:175], v[198:201], v[120:123]
	v_mfma_f32_16x16x32_bf16 v[108:111], v[164:167], v[206:209], v[108:111]
	v_mfma_f32_16x16x32_bf16 v[104:107], v[172:175], v[206:209], v[104:107]
	v_mfma_f32_16x16x32_bf16 v[92:95], v[164:167], v[214:217], v[92:95]
	v_mfma_f32_16x16x32_bf16 v[88:91], v[172:175], v[214:217], v[88:91]
	v_mfma_f32_16x16x32_bf16 v[76:79], v[164:167], v[222:225], v[76:79]
	v_mfma_f32_16x16x32_bf16 v[72:75], v[172:175], v[222:225], v[72:75]
	v_mfma_f32_16x16x32_bf16 v[116:119], v[176:179], v[194:197], v[116:119]
	v_mfma_f32_16x16x32_bf16 v[112:115], v[184:187], v[194:197], v[112:115]
	v_mfma_f32_16x16x32_bf16 v[100:103], v[176:179], v[202:205], v[100:103]
	v_mfma_f32_16x16x32_bf16 v[96:99], v[184:187], v[202:205], v[96:99]
	v_mfma_f32_16x16x32_bf16 v[84:87], v[176:179], v[210:213], v[84:87]
	v_mfma_f32_16x16x32_bf16 v[80:83], v[184:187], v[210:213], v[80:83]
	v_mfma_f32_16x16x32_bf16 v[68:71], v[176:179], v[218:221], v[68:71]
	v_mfma_f32_16x16x32_bf16 v[64:67], v[184:187], v[218:221], v[64:67]
	v_mfma_f32_16x16x32_bf16 v[116:119], v[180:183], v[198:201], v[116:119]
	v_mfma_f32_16x16x32_bf16 v[112:115], v[190:193], v[198:201], v[112:115]
	v_mfma_f32_16x16x32_bf16 v[100:103], v[180:183], v[206:209], v[100:103]
	v_mfma_f32_16x16x32_bf16 v[96:99], v[190:193], v[206:209], v[96:99]
	v_mfma_f32_16x16x32_bf16 v[84:87], v[180:183], v[214:217], v[84:87]
	v_mfma_f32_16x16x32_bf16 v[80:83], v[190:193], v[214:217], v[80:83]
	v_mfma_f32_16x16x32_bf16 v[68:71], v[180:183], v[222:225], v[68:71]
	v_mfma_f32_16x16x32_bf16 v[64:67], v[190:193], v[222:225], v[64:67]
	s_barrier
	s_add_u32 s98, s44, 0x80
	s_addc_u32 s99, s45, 0
	s_add_u32 s100, s46, 0xfff80080
	s_addc_u32 s101, s47, -1
	s_add_i32 s46, s63, s26
	s_mov_b32 m0, s46
	ds_read_b128 v[194:197], v161 offset:49152
	ds_read_b128 v[198:201], v161 offset:50176
	ds_read_b128 v[202:205], v161 offset:51200
	ds_read_b128 v[206:209], v161 offset:52224
	ds_read_b128 v[210:213], v161 offset:53248
	ds_read_b128 v[214:217], v161 offset:54272
	ds_read_b128 v[218:221], v161 offset:55296
	ds_read_b128 v[222:225], v161 offset:56320
	global_load_lds_dwordx4 v130, s[98:99]
	s_add_i32 m0, s46, 0x2000
	s_add_u32 s44, s44, 0x80080
	s_addc_u32 s45, s45, 0
	s_add_i32 s46, s64, s26
	global_load_lds_dwordx4 v134, s[98:99]
	s_mov_b32 m0, s46
	s_nop 0
	global_load_lds_dwordx4 v130, s[44:45]
	s_add_i32 m0, s46, 0x2000
	s_nop 0
	global_load_lds_dwordx4 v134, s[44:45]
	s_mov_b32 m0, s50
	s_nop 0
	global_load_lds_dwordx4 v128, s[100:101]
	s_mov_b32 m0, s51
	s_nop 0
	global_load_lds_dwordx4 v132, s[100:101]
	s_waitcnt vmcnt(8)
	s_waitcnt lgkmcnt(0)
	s_barrier
	s_waitcnt lgkmcnt(0)
	v_mfma_f32_16x16x32_bf16 v[60:63], v[154:157], v[194:197], v[60:63]
	v_mfma_f32_16x16x32_bf16 v[56:59], v[168:171], v[194:197], v[56:59]
	v_mfma_f32_16x16x32_bf16 v[44:47], v[154:157], v[202:205], v[44:47]
	v_mfma_f32_16x16x32_bf16 v[40:43], v[168:171], v[202:205], v[40:43]
	v_mfma_f32_16x16x32_bf16 v[28:31], v[154:157], v[210:213], v[28:31]
	v_mfma_f32_16x16x32_bf16 v[24:27], v[168:171], v[210:213], v[24:27]
	v_mfma_f32_16x16x32_bf16 v[12:15], v[154:157], v[218:221], v[12:15]
	v_mfma_f32_16x16x32_bf16 v[8:11], v[168:171], v[218:221], v[8:11]
	v_mfma_f32_16x16x32_bf16 v[60:63], v[164:167], v[198:201], v[60:63]
	v_mfma_f32_16x16x32_bf16 v[56:59], v[172:175], v[198:201], v[56:59]
	v_mfma_f32_16x16x32_bf16 v[44:47], v[164:167], v[206:209], v[44:47]
	v_mfma_f32_16x16x32_bf16 v[40:43], v[172:175], v[206:209], v[40:43]
	v_mfma_f32_16x16x32_bf16 v[28:31], v[164:167], v[214:217], v[28:31]
	v_mfma_f32_16x16x32_bf16 v[24:27], v[172:175], v[214:217], v[24:27]
	v_mfma_f32_16x16x32_bf16 v[12:15], v[164:167], v[222:225], v[12:15]
	v_mfma_f32_16x16x32_bf16 v[8:11], v[172:175], v[222:225], v[8:11]
	v_mfma_f32_16x16x32_bf16 v[52:55], v[176:179], v[194:197], v[52:55]
	v_mfma_f32_16x16x32_bf16 v[48:51], v[184:187], v[194:197], v[48:51]
	v_mfma_f32_16x16x32_bf16 v[36:39], v[176:179], v[202:205], v[36:39]
	v_mfma_f32_16x16x32_bf16 v[32:35], v[184:187], v[202:205], v[32:35]
	v_mfma_f32_16x16x32_bf16 v[20:23], v[176:179], v[210:213], v[20:23]
	v_mfma_f32_16x16x32_bf16 v[16:19], v[184:187], v[210:213], v[16:19]
	v_mfma_f32_16x16x32_bf16 v[4:7], v[176:179], v[218:221], v[4:7]
	v_mfma_f32_16x16x32_bf16 v[0:3], v[184:187], v[218:221], v[0:3]
	v_mfma_f32_16x16x32_bf16 v[52:55], v[180:183], v[198:201], v[52:55]
	v_mfma_f32_16x16x32_bf16 v[48:51], v[190:193], v[198:201], v[48:51]
	v_mfma_f32_16x16x32_bf16 v[36:39], v[180:183], v[206:209], v[36:39]
	v_mfma_f32_16x16x32_bf16 v[32:35], v[190:193], v[206:209], v[32:35]
	v_mfma_f32_16x16x32_bf16 v[20:23], v[180:183], v[214:217], v[20:23]
	v_mfma_f32_16x16x32_bf16 v[16:19], v[190:193], v[214:217], v[16:19]
	v_mfma_f32_16x16x32_bf16 v[4:7], v[180:183], v[222:225], v[4:7]
	v_mfma_f32_16x16x32_bf16 v[0:3], v[190:193], v[222:225], v[0:3]
	s_barrier
	s_add_i32 s62, s62, 2
	s_add_u32 s10, s10, 0x100
	s_addc_u32 s11, s11, 0
	s_add_u32 s60, s60, 0x100
	s_addc_u32 s61, s61, 0
	s_cmp_gt_u32 s62, 29
	s_cbranch_scc0 .LBB0_838
	s_and_b64 vcc, exec, s[20:21]
	s_cbranch_vccnz .LBB0_843
	v_lshl_add_u32 v154, s6, 8, v158
	s_cmp_gt_i32 s42, 3
	s_mov_b64 s[6:7], -1
	s_cbranch_scc1 .LBB0_844

.LBB0_947:
	ds_read_b128 v[154:157], v137
	ds_read_b128 v[158:161], v137 offset:1024
	ds_read_b128 v[174:177], v137 offset:2048
	ds_read_b128 v[178:181], v137 offset:3072
	ds_read_b128 v[182:185], v170
	ds_read_b128 v[190:193], v170 offset:1024
	ds_read_b128 v[194:197], v170 offset:2048
	ds_read_b128 v[198:201], v170 offset:3072
	s_add_u32 s34, s10, 0xfffe0080
	s_addc_u32 s35, s11, -1
	s_cmp_eq_u32 s53, 4
	s_cselect_b32 s37, s5, s35
	s_cselect_b32 s36, s9, s34
	s_cselect_b32 s35, s13, s52
	s_cselect_b32 s34, s16, s51
	s_add_i32 m0, s15, 0xc000
	ds_read_b128 v[202:205], v171
	ds_read_b128 v[206:209], v171 offset:1024
	ds_read_b128 v[210:213], v171 offset:2048
	ds_read_b128 v[214:217], v171 offset:3072
	ds_read_b128 v[218:221], v171 offset:4096
	ds_read_b128 v[222:225], v171 offset:5120
	ds_read_b128 v[226:229], v171 offset:6144
	ds_read_b128 v[230:233], v171 offset:7168
	global_load_lds_dwordx4 v146, s[10:11]
	s_add_i32 m0, s15, 0xe000
	s_nop 0
	global_load_lds_dwordx4 v148, s[10:11]
	s_waitcnt vmcnt(8)
	s_waitcnt lgkmcnt(0)
	s_barrier
	s_waitcnt lgkmcnt(0)
	v_mfma_f32_16x16x32_bf16 v[124:127], v[154:157], v[202:205], v[124:127]
	v_mfma_f32_16x16x32_bf16 v[120:123], v[174:177], v[202:205], v[120:123]
	v_mfma_f32_16x16x32_bf16 v[108:111], v[154:157], v[210:213], v[108:111]
	v_mfma_f32_16x16x32_bf16 v[104:107], v[174:177], v[210:213], v[104:107]
	v_mfma_f32_16x16x32_bf16 v[92:95], v[154:157], v[218:221], v[92:95]
	v_mfma_f32_16x16x32_bf16 v[88:91], v[174:177], v[218:221], v[88:91]
	v_mfma_f32_16x16x32_bf16 v[76:79], v[154:157], v[226:229], v[76:79]
	v_mfma_f32_16x16x32_bf16 v[72:75], v[174:177], v[226:229], v[72:75]
	v_mfma_f32_16x16x32_bf16 v[124:127], v[158:161], v[206:209], v[124:127]
	v_mfma_f32_16x16x32_bf16 v[120:123], v[178:181], v[206:209], v[120:123]
	v_mfma_f32_16x16x32_bf16 v[108:111], v[158:161], v[214:217], v[108:111]
	v_mfma_f32_16x16x32_bf16 v[104:107], v[178:181], v[214:217], v[104:107]
	v_mfma_f32_16x16x32_bf16 v[92:95], v[158:161], v[222:225], v[92:95]
	v_mfma_f32_16x16x32_bf16 v[88:91], v[178:181], v[222:225], v[88:91]
	v_mfma_f32_16x16x32_bf16 v[76:79], v[158:161], v[230:233], v[76:79]
	v_mfma_f32_16x16x32_bf16 v[72:75], v[178:181], v[230:233], v[72:75]
	v_mfma_f32_16x16x32_bf16 v[116:119], v[182:185], v[202:205], v[116:119]
	v_mfma_f32_16x16x32_bf16 v[112:115], v[194:197], v[202:205], v[112:115]
	v_mfma_f32_16x16x32_bf16 v[100:103], v[182:185], v[210:213], v[100:103]
	v_mfma_f32_16x16x32_bf16 v[96:99], v[194:197], v[210:213], v[96:99]
	v_mfma_f32_16x16x32_bf16 v[84:87], v[182:185], v[218:221], v[84:87]
	v_mfma_f32_16x16x32_bf16 v[80:83], v[194:197], v[218:221], v[80:83]
	v_mfma_f32_16x16x32_bf16 v[68:71], v[182:185], v[226:229], v[68:71]
	v_mfma_f32_16x16x32_bf16 v[64:67], v[194:197], v[226:229], v[64:67]
	v_mfma_f32_16x16x32_bf16 v[116:119], v[190:193], v[206:209], v[116:119]
	v_mfma_f32_16x16x32_bf16 v[112:115], v[198:201], v[206:209], v[112:115]
	v_mfma_f32_16x16x32_bf16 v[100:103], v[190:193], v[214:217], v[100:103]
	v_mfma_f32_16x16x32_bf16 v[96:99], v[198:201], v[214:217], v[96:99]
	v_mfma_f32_16x16x32_bf16 v[84:87], v[190:193], v[222:225], v[84:87]
	v_mfma_f32_16x16x32_bf16 v[80:83], v[198:201], v[222:225], v[80:83]
	v_mfma_f32_16x16x32_bf16 v[68:71], v[190:193], v[230:233], v[68:71]
	v_mfma_f32_16x16x32_bf16 v[64:67], v[198:201], v[230:233], v[64:67]
	s_barrier
	s_add_i32 s54, s47, s26
	s_mov_b32 m0, s54
	ds_read_b128 v[202:205], v171 offset:16384
	ds_read_b128 v[206:209], v171 offset:17408
	ds_read_b128 v[210:213], v171 offset:18432
	ds_read_b128 v[214:217], v171 offset:19456
	ds_read_b128 v[218:221], v171 offset:20480
	ds_read_b128 v[222:225], v171 offset:21504
	ds_read_b128 v[226:229], v171 offset:22528
	ds_read_b128 v[230:233], v171 offset:23552
	global_load_lds_dwordx4 v130, s[34:35]
	s_add_i32 m0, s54, 0x2000
	s_add_u32 s54, s34, 0x20000
	s_addc_u32 s55, s35, 0
	s_add_i32 s58, s48, s26
	global_load_lds_dwordx4 v134, s[34:35]
	s_mov_b32 m0, s58
	s_nop 0
	global_load_lds_dwordx4 v130, s[54:55]
	s_add_i32 m0, s58, 0x2000
	s_nop 0
	global_load_lds_dwordx4 v134, s[54:55]
	s_mov_b32 m0, s15
	s_nop 0
	global_load_lds_dwordx4 v128, s[36:37]
	s_mov_b32 m0, s27
	s_nop 0
	global_load_lds_dwordx4 v132, s[36:37]
	s_waitcnt vmcnt(8)
	s_waitcnt lgkmcnt(0)
	s_barrier
	s_waitcnt lgkmcnt(0)
	v_mfma_f32_16x16x32_bf16 v[60:63], v[154:157], v[202:205], v[60:63]
	v_mfma_f32_16x16x32_bf16 v[56:59], v[174:177], v[202:205], v[56:59]
	v_mfma_f32_16x16x32_bf16 v[44:47], v[154:157], v[210:213], v[44:47]
	v_mfma_f32_16x16x32_bf16 v[40:43], v[174:177], v[210:213], v[40:43]
	v_mfma_f32_16x16x32_bf16 v[28:31], v[154:157], v[218:221], v[28:31]
	v_mfma_f32_16x16x32_bf16 v[24:27], v[174:177], v[218:221], v[24:27]
	v_mfma_f32_16x16x32_bf16 v[12:15], v[154:157], v[226:229], v[12:15]
	v_mfma_f32_16x16x32_bf16 v[8:11], v[174:177], v[226:229], v[8:11]
	v_mfma_f32_16x16x32_bf16 v[60:63], v[158:161], v[206:209], v[60:63]
	v_mfma_f32_16x16x32_bf16 v[56:59], v[178:181], v[206:209], v[56:59]
	v_mfma_f32_16x16x32_bf16 v[44:47], v[158:161], v[214:217], v[44:47]
	v_mfma_f32_16x16x32_bf16 v[40:43], v[178:181], v[214:217], v[40:43]
	v_mfma_f32_16x16x32_bf16 v[28:31], v[158:161], v[222:225], v[28:31]
	v_mfma_f32_16x16x32_bf16 v[24:27], v[178:181], v[222:225], v[24:27]
	v_mfma_f32_16x16x32_bf16 v[12:15], v[158:161], v[230:233], v[12:15]
	v_mfma_f32_16x16x32_bf16 v[8:11], v[178:181], v[230:233], v[8:11]
	v_mfma_f32_16x16x32_bf16 v[52:55], v[182:185], v[202:205], v[52:55]
	v_mfma_f32_16x16x32_bf16 v[48:51], v[194:197], v[202:205], v[48:51]
	v_mfma_f32_16x16x32_bf16 v[36:39], v[182:185], v[210:213], v[36:39]
	v_mfma_f32_16x16x32_bf16 v[32:35], v[194:197], v[210:213], v[32:35]
	v_mfma_f32_16x16x32_bf16 v[20:23], v[182:185], v[218:221], v[20:23]
	v_mfma_f32_16x16x32_bf16 v[16:19], v[194:197], v[218:221], v[16:19]
	v_mfma_f32_16x16x32_bf16 v[4:7], v[182:185], v[226:229], v[4:7]
	v_mfma_f32_16x16x32_bf16 v[0:3], v[194:197], v[226:229], v[0:3]
	v_mfma_f32_16x16x32_bf16 v[52:55], v[190:193], v[206:209], v[52:55]
	v_mfma_f32_16x16x32_bf16 v[48:51], v[198:201], v[206:209], v[48:51]
	v_mfma_f32_16x16x32_bf16 v[36:39], v[190:193], v[214:217], v[36:39]
	v_mfma_f32_16x16x32_bf16 v[32:35], v[198:201], v[214:217], v[32:35]
	v_mfma_f32_16x16x32_bf16 v[20:23], v[190:193], v[222:225], v[20:23]
	v_mfma_f32_16x16x32_bf16 v[16:19], v[198:201], v[222:225], v[16:19]
	v_mfma_f32_16x16x32_bf16 v[4:7], v[190:193], v[230:233], v[4:7]
	v_mfma_f32_16x16x32_bf16 v[0:3], v[198:201], v[230:233], v[0:3]
	s_barrier
	s_add_i32 s54, 0, 0x18000
	v_add_u32_e32 v138, s54, v169
	s_add_i32 s55, 0, 0x1c000
	ds_read_b128 v[154:157], v138
	ds_read_b128 v[158:161], v138 offset:1024
	ds_read_b128 v[174:177], v138 offset:2048
	ds_read_b128 v[178:181], v138 offset:3072
	v_add_u32_e32 v138, s55, v169
	ds_read_b128 v[182:185], v138
	ds_read_b128 v[190:193], v138 offset:1024
	ds_read_b128 v[194:197], v138 offset:2048
	ds_read_b128 v[198:201], v138 offset:3072
	s_add_u32 s36, s36, 0x20000
	s_addc_u32 s37, s37, 0
	s_mov_b32 m0, s38
	ds_read_b128 v[202:205], v171 offset:32768
	ds_read_b128 v[206:209], v171 offset:33792
	ds_read_b128 v[210:213], v171 offset:34816
	ds_read_b128 v[214:217], v171 offset:35840
	ds_read_b128 v[218:221], v171 offset:36864
	ds_read_b128 v[222:225], v171 offset:37888
	ds_read_b128 v[226:229], v171 offset:38912
	ds_read_b128 v[230:233], v171 offset:39936
	global_load_lds_dwordx4 v128, s[36:37]
	s_mov_b32 m0, s39
	s_nop 0
	global_load_lds_dwordx4 v132, s[36:37]
	s_waitcnt vmcnt(8)
	s_waitcnt lgkmcnt(0)
	s_barrier
	s_waitcnt lgkmcnt(0)
	v_mfma_f32_16x16x32_bf16 v[124:127], v[154:157], v[202:205], v[124:127]
	v_mfma_f32_16x16x32_bf16 v[120:123], v[174:177], v[202:205], v[120:123]
	v_mfma_f32_16x16x32_bf16 v[108:111], v[154:157], v[210:213], v[108:111]
	v_mfma_f32_16x16x32_bf16 v[104:107], v[174:177], v[210:213], v[104:107]
	v_mfma_f32_16x16x32_bf16 v[92:95], v[154:157], v[218:221], v[92:95]
	v_mfma_f32_16x16x32_bf16 v[88:91], v[174:177], v[218:221], v[88:91]
	v_mfma_f32_16x16x32_bf16 v[76:79], v[154:157], v[226:229], v[76:79]
	v_mfma_f32_16x16x32_bf16 v[72:75], v[174:177], v[226:229], v[72:75]
	v_mfma_f32_16x16x32_bf16 v[124:127], v[158:161], v[206:209], v[124:127]
	v_mfma_f32_16x16x32_bf16 v[120:123], v[178:181], v[206:209], v[120:123]
	v_mfma_f32_16x16x32_bf16 v[108:111], v[158:161], v[214:217], v[108:111]
	v_mfma_f32_16x16x32_bf16 v[104:107], v[178:181], v[214:217], v[104:107]
	v_mfma_f32_16x16x32_bf16 v[92:95], v[158:161], v[222:225], v[92:95]
	v_mfma_f32_16x16x32_bf16 v[88:91], v[178:181], v[222:225], v[88:91]
	v_mfma_f32_16x16x32_bf16 v[76:79], v[158:161], v[230:233], v[76:79]
	v_mfma_f32_16x16x32_bf16 v[72:75], v[178:181], v[230:233], v[72:75]
	v_mfma_f32_16x16x32_bf16 v[116:119], v[182:185], v[202:205], v[116:119]
	v_mfma_f32_16x16x32_bf16 v[112:115], v[194:197], v[202:205], v[112:115]
	v_mfma_f32_16x16x32_bf16 v[100:103], v[182:185], v[210:213], v[100:103]
	v_mfma_f32_16x16x32_bf16 v[96:99], v[194:197], v[210:213], v[96:99]
	v_mfma_f32_16x16x32_bf16 v[84:87], v[182:185], v[218:221], v[84:87]
	v_mfma_f32_16x16x32_bf16 v[80:83], v[194:197], v[218:221], v[80:83]
	v_mfma_f32_16x16x32_bf16 v[68:71], v[182:185], v[226:229], v[68:71]
	v_mfma_f32_16x16x32_bf16 v[64:67], v[194:197], v[226:229], v[64:67]
	v_mfma_f32_16x16x32_bf16 v[116:119], v[190:193], v[206:209], v[116:119]
	v_mfma_f32_16x16x32_bf16 v[112:115], v[198:201], v[206:209], v[112:115]
	v_mfma_f32_16x16x32_bf16 v[100:103], v[190:193], v[214:217], v[100:103]
	v_mfma_f32_16x16x32_bf16 v[96:99], v[198:201], v[214:217], v[96:99]
	v_mfma_f32_16x16x32_bf16 v[84:87], v[190:193], v[222:225], v[84:87]
	v_mfma_f32_16x16x32_bf16 v[80:83], v[198:201], v[222:225], v[80:83]
	v_mfma_f32_16x16x32_bf16 v[68:71], v[190:193], v[230:233], v[68:71]
	v_mfma_f32_16x16x32_bf16 v[64:67], v[198:201], v[230:233], v[64:67]
	s_barrier
	s_add_u32 s98, s34, 0x80
	s_addc_u32 s99, s35, 0
	s_add_u32 s100, s36, 0xfffe0080
	s_addc_u32 s101, s37, -1
	s_add_i32 s36, s54, s26
	s_mov_b32 m0, s36
	ds_read_b128 v[202:205], v171 offset:49152
	ds_read_b128 v[206:209], v171 offset:50176
	ds_read_b128 v[210:213], v171 offset:51200
	ds_read_b128 v[214:217], v171 offset:52224
	ds_read_b128 v[218:221], v171 offset:53248
	ds_read_b128 v[222:225], v171 offset:54272
	ds_read_b128 v[226:229], v171 offset:55296
	ds_read_b128 v[230:233], v171 offset:56320
	global_load_lds_dwordx4 v130, s[98:99]
	s_add_i32 m0, s36, 0x2000
	s_add_u32 s34, s34, 0x20080
	s_addc_u32 s35, s35, 0
	s_add_i32 s36, s55, s26
	global_load_lds_dwordx4 v134, s[98:99]
	s_mov_b32 m0, s36
	s_nop 0
	global_load_lds_dwordx4 v130, s[34:35]
	s_add_i32 m0, s36, 0x2000
	s_nop 0
	global_load_lds_dwordx4 v134, s[34:35]
	s_mov_b32 m0, s41
	s_nop 0
	global_load_lds_dwordx4 v128, s[100:101]
	s_mov_b32 m0, s42
	s_nop 0
	global_load_lds_dwordx4 v132, s[100:101]
	s_waitcnt vmcnt(8)
	s_waitcnt lgkmcnt(0)
	s_barrier
	s_waitcnt lgkmcnt(0)
	v_mfma_f32_16x16x32_bf16 v[60:63], v[154:157], v[202:205], v[60:63]
	v_mfma_f32_16x16x32_bf16 v[56:59], v[174:177], v[202:205], v[56:59]
	v_mfma_f32_16x16x32_bf16 v[44:47], v[154:157], v[210:213], v[44:47]
	v_mfma_f32_16x16x32_bf16 v[40:43], v[174:177], v[210:213], v[40:43]
	v_mfma_f32_16x16x32_bf16 v[28:31], v[154:157], v[218:221], v[28:31]
	v_mfma_f32_16x16x32_bf16 v[24:27], v[174:177], v[218:221], v[24:27]
	v_mfma_f32_16x16x32_bf16 v[12:15], v[154:157], v[226:229], v[12:15]
	v_mfma_f32_16x16x32_bf16 v[8:11], v[174:177], v[226:229], v[8:11]
	v_mfma_f32_16x16x32_bf16 v[60:63], v[158:161], v[206:209], v[60:63]
	v_mfma_f32_16x16x32_bf16 v[56:59], v[178:181], v[206:209], v[56:59]
	v_mfma_f32_16x16x32_bf16 v[44:47], v[158:161], v[214:217], v[44:47]
	v_mfma_f32_16x16x32_bf16 v[40:43], v[178:181], v[214:217], v[40:43]
	v_mfma_f32_16x16x32_bf16 v[28:31], v[158:161], v[222:225], v[28:31]
	v_mfma_f32_16x16x32_bf16 v[24:27], v[178:181], v[222:225], v[24:27]
	v_mfma_f32_16x16x32_bf16 v[12:15], v[158:161], v[230:233], v[12:15]
	v_mfma_f32_16x16x32_bf16 v[8:11], v[178:181], v[230:233], v[8:11]
	v_mfma_f32_16x16x32_bf16 v[52:55], v[182:185], v[202:205], v[52:55]
	v_mfma_f32_16x16x32_bf16 v[48:51], v[194:197], v[202:205], v[48:51]
	v_mfma_f32_16x16x32_bf16 v[36:39], v[182:185], v[210:213], v[36:39]
	v_mfma_f32_16x16x32_bf16 v[32:35], v[194:197], v[210:213], v[32:35]
	v_mfma_f32_16x16x32_bf16 v[20:23], v[182:185], v[218:221], v[20:23]
	v_mfma_f32_16x16x32_bf16 v[16:19], v[194:197], v[218:221], v[16:19]
	v_mfma_f32_16x16x32_bf16 v[4:7], v[182:185], v[226:229], v[4:7]
	v_mfma_f32_16x16x32_bf16 v[0:3], v[194:197], v[226:229], v[0:3]
	v_mfma_f32_16x16x32_bf16 v[52:55], v[190:193], v[206:209], v[52:55]
	v_mfma_f32_16x16x32_bf16 v[48:51], v[198:201], v[206:209], v[48:51]
	v_mfma_f32_16x16x32_bf16 v[36:39], v[190:193], v[214:217], v[36:39]
	v_mfma_f32_16x16x32_bf16 v[32:35], v[198:201], v[214:217], v[32:35]
	v_mfma_f32_16x16x32_bf16 v[20:23], v[190:193], v[222:225], v[20:23]
	v_mfma_f32_16x16x32_bf16 v[16:19], v[198:201], v[222:225], v[16:19]
	v_mfma_f32_16x16x32_bf16 v[4:7], v[190:193], v[230:233], v[4:7]
	v_mfma_f32_16x16x32_bf16 v[0:3], v[198:201], v[230:233], v[0:3]
	s_barrier
	s_add_i32 s53, s53, 2
	s_add_u32 s10, s10, 0x100
	s_addc_u32 s11, s11, 0
	s_add_u32 s51, s51, 0x100
	s_addc_u32 s52, s52, 0
	s_cmp_gt_u32 s53, 5
	s_cbranch_scc0 .LBB0_947
	s_and_b64 vcc, exec, s[22:23]
	s_cbranch_vccz .LBB0_950
	s_barrier

.LBB0_1037:
	ds_read_b128 v[148:151], v160
	ds_read_b128 v[152:155], v160 offset:1024
	ds_read_b128 v[166:169], v160 offset:2048
	ds_read_b128 v[170:173], v160 offset:3072
	ds_read_b128 v[174:177], v161
	ds_read_b128 v[178:181], v161 offset:1024
	ds_read_b128 v[182:185], v161 offset:2048
	ds_read_b128 v[190:193], v161 offset:3072
	s_add_u32 s34, s10, 0xfffe0080
	s_addc_u32 s35, s11, -1
	s_cmp_eq_u32 s51, 4
	s_cselect_b32 s37, s5, s35
	s_cselect_b32 s36, s12, s34
	s_cselect_b32 s35, s23, s50
	s_cselect_b32 s34, s27, s49
	s_add_i32 m0, s9, 0xc000
	ds_read_b128 v[194:197], v162
	ds_read_b128 v[198:201], v162 offset:1024
	ds_read_b128 v[202:205], v162 offset:2048
	ds_read_b128 v[206:209], v162 offset:3072
	ds_read_b128 v[210:213], v162 offset:4096
	ds_read_b128 v[214:217], v162 offset:5120
	ds_read_b128 v[218:221], v162 offset:6144
	ds_read_b128 v[222:225], v162 offset:7168
	global_load_lds_dwordx4 v140, s[10:11]
	s_add_i32 m0, s9, 0xe000
	s_nop 0
	global_load_lds_dwordx4 v142, s[10:11]
	s_waitcnt vmcnt(8)
	s_waitcnt lgkmcnt(0)
	s_barrier
	s_waitcnt lgkmcnt(0)
	v_mfma_f32_16x16x32_bf16 v[124:127], v[148:151], v[194:197], v[124:127]
	v_mfma_f32_16x16x32_bf16 v[120:123], v[166:169], v[194:197], v[120:123]
	v_mfma_f32_16x16x32_bf16 v[108:111], v[148:151], v[202:205], v[108:111]
	v_mfma_f32_16x16x32_bf16 v[104:107], v[166:169], v[202:205], v[104:107]
	v_mfma_f32_16x16x32_bf16 v[92:95], v[148:151], v[210:213], v[92:95]
	v_mfma_f32_16x16x32_bf16 v[88:91], v[166:169], v[210:213], v[88:91]
	v_mfma_f32_16x16x32_bf16 v[76:79], v[148:151], v[218:221], v[76:79]
	v_mfma_f32_16x16x32_bf16 v[72:75], v[166:169], v[218:221], v[72:75]
	v_mfma_f32_16x16x32_bf16 v[124:127], v[152:155], v[198:201], v[124:127]
	v_mfma_f32_16x16x32_bf16 v[120:123], v[170:173], v[198:201], v[120:123]
	v_mfma_f32_16x16x32_bf16 v[108:111], v[152:155], v[206:209], v[108:111]
	v_mfma_f32_16x16x32_bf16 v[104:107], v[170:173], v[206:209], v[104:107]
	v_mfma_f32_16x16x32_bf16 v[92:95], v[152:155], v[214:217], v[92:95]
	v_mfma_f32_16x16x32_bf16 v[88:91], v[170:173], v[214:217], v[88:91]
	v_mfma_f32_16x16x32_bf16 v[76:79], v[152:155], v[222:225], v[76:79]
	v_mfma_f32_16x16x32_bf16 v[72:75], v[170:173], v[222:225], v[72:75]
	v_mfma_f32_16x16x32_bf16 v[116:119], v[174:177], v[194:197], v[116:119]
	v_mfma_f32_16x16x32_bf16 v[112:115], v[182:185], v[194:197], v[112:115]
	v_mfma_f32_16x16x32_bf16 v[100:103], v[174:177], v[202:205], v[100:103]
	v_mfma_f32_16x16x32_bf16 v[96:99], v[182:185], v[202:205], v[96:99]
	v_mfma_f32_16x16x32_bf16 v[84:87], v[174:177], v[210:213], v[84:87]
	v_mfma_f32_16x16x32_bf16 v[80:83], v[182:185], v[210:213], v[80:83]
	v_mfma_f32_16x16x32_bf16 v[68:71], v[174:177], v[218:221], v[68:71]
	v_mfma_f32_16x16x32_bf16 v[64:67], v[182:185], v[218:221], v[64:67]
	v_mfma_f32_16x16x32_bf16 v[116:119], v[178:181], v[198:201], v[116:119]
	v_mfma_f32_16x16x32_bf16 v[112:115], v[190:193], v[198:201], v[112:115]
	v_mfma_f32_16x16x32_bf16 v[100:103], v[178:181], v[206:209], v[100:103]
	v_mfma_f32_16x16x32_bf16 v[96:99], v[190:193], v[206:209], v[96:99]
	v_mfma_f32_16x16x32_bf16 v[84:87], v[178:181], v[214:217], v[84:87]
	v_mfma_f32_16x16x32_bf16 v[80:83], v[190:193], v[214:217], v[80:83]
	v_mfma_f32_16x16x32_bf16 v[68:71], v[178:181], v[222:225], v[68:71]
	v_mfma_f32_16x16x32_bf16 v[64:67], v[190:193], v[222:225], v[64:67]
	s_barrier
	s_add_i32 s52, s45, s24
	s_mov_b32 m0, s52
	ds_read_b128 v[194:197], v162 offset:16384
	ds_read_b128 v[198:201], v162 offset:17408
	ds_read_b128 v[202:205], v162 offset:18432
	ds_read_b128 v[206:209], v162 offset:19456
	ds_read_b128 v[210:213], v162 offset:20480
	ds_read_b128 v[214:217], v162 offset:21504
	ds_read_b128 v[218:221], v162 offset:22528
	ds_read_b128 v[222:225], v162 offset:23552
	global_load_lds_dwordx4 v130, s[34:35]
	s_add_i32 m0, s52, 0x2000
	s_add_u32 s52, s34, 0x20000
	s_addc_u32 s53, s35, 0
	s_add_i32 s54, s46, s24
	global_load_lds_dwordx4 v134, s[34:35]
	s_mov_b32 m0, s54
	s_nop 0
	global_load_lds_dwordx4 v130, s[52:53]
	s_add_i32 m0, s54, 0x2000
	s_nop 0
	global_load_lds_dwordx4 v134, s[52:53]
	s_mov_b32 m0, s9
	s_nop 0
	global_load_lds_dwordx4 v128, s[36:37]
	s_mov_b32 m0, s25
	s_nop 0
	global_load_lds_dwordx4 v132, s[36:37]
	s_waitcnt vmcnt(8)
	s_waitcnt lgkmcnt(0)
	s_barrier
	s_waitcnt lgkmcnt(0)
	v_mfma_f32_16x16x32_bf16 v[60:63], v[148:151], v[194:197], v[60:63]
	v_mfma_f32_16x16x32_bf16 v[56:59], v[166:169], v[194:197], v[56:59]
	v_mfma_f32_16x16x32_bf16 v[44:47], v[148:151], v[202:205], v[44:47]
	v_mfma_f32_16x16x32_bf16 v[40:43], v[166:169], v[202:205], v[40:43]
	v_mfma_f32_16x16x32_bf16 v[28:31], v[148:151], v[210:213], v[28:31]
	v_mfma_f32_16x16x32_bf16 v[24:27], v[166:169], v[210:213], v[24:27]
	v_mfma_f32_16x16x32_bf16 v[12:15], v[148:151], v[218:221], v[12:15]
	v_mfma_f32_16x16x32_bf16 v[8:11], v[166:169], v[218:221], v[8:11]
	v_mfma_f32_16x16x32_bf16 v[60:63], v[152:155], v[198:201], v[60:63]
	v_mfma_f32_16x16x32_bf16 v[56:59], v[170:173], v[198:201], v[56:59]
	v_mfma_f32_16x16x32_bf16 v[44:47], v[152:155], v[206:209], v[44:47]
	v_mfma_f32_16x16x32_bf16 v[40:43], v[170:173], v[206:209], v[40:43]
	v_mfma_f32_16x16x32_bf16 v[28:31], v[152:155], v[214:217], v[28:31]
	v_mfma_f32_16x16x32_bf16 v[24:27], v[170:173], v[214:217], v[24:27]
	v_mfma_f32_16x16x32_bf16 v[12:15], v[152:155], v[222:225], v[12:15]
	v_mfma_f32_16x16x32_bf16 v[8:11], v[170:173], v[222:225], v[8:11]
	v_mfma_f32_16x16x32_bf16 v[52:55], v[174:177], v[194:197], v[52:55]
	v_mfma_f32_16x16x32_bf16 v[48:51], v[182:185], v[194:197], v[48:51]
	v_mfma_f32_16x16x32_bf16 v[36:39], v[174:177], v[202:205], v[36:39]
	v_mfma_f32_16x16x32_bf16 v[32:35], v[182:185], v[202:205], v[32:35]
	v_mfma_f32_16x16x32_bf16 v[20:23], v[174:177], v[210:213], v[20:23]
	v_mfma_f32_16x16x32_bf16 v[16:19], v[182:185], v[210:213], v[16:19]
	v_mfma_f32_16x16x32_bf16 v[4:7], v[174:177], v[218:221], v[4:7]
	v_mfma_f32_16x16x32_bf16 v[0:3], v[182:185], v[218:221], v[0:3]
	v_mfma_f32_16x16x32_bf16 v[52:55], v[178:181], v[198:201], v[52:55]
	v_mfma_f32_16x16x32_bf16 v[48:51], v[190:193], v[198:201], v[48:51]
	v_mfma_f32_16x16x32_bf16 v[36:39], v[178:181], v[206:209], v[36:39]
	v_mfma_f32_16x16x32_bf16 v[32:35], v[190:193], v[206:209], v[32:35]
	v_mfma_f32_16x16x32_bf16 v[20:23], v[178:181], v[214:217], v[20:23]
	v_mfma_f32_16x16x32_bf16 v[16:19], v[190:193], v[214:217], v[16:19]
	v_mfma_f32_16x16x32_bf16 v[4:7], v[178:181], v[222:225], v[4:7]
	v_mfma_f32_16x16x32_bf16 v[0:3], v[190:193], v[222:225], v[0:3]
	s_barrier
	s_add_i32 s52, 0, 0x18000
	v_add_u32_e32 v165, s52, v159
	s_add_i32 s53, 0, 0x1c000
	ds_read_b128 v[148:151], v165
	ds_read_b128 v[152:155], v165 offset:1024
	ds_read_b128 v[166:169], v165 offset:2048
	ds_read_b128 v[170:173], v165 offset:3072
	v_add_u32_e32 v165, s53, v159
	ds_read_b128 v[174:177], v165
	ds_read_b128 v[178:181], v165 offset:1024
	ds_read_b128 v[182:185], v165 offset:2048
	ds_read_b128 v[190:193], v165 offset:3072
	s_add_u32 s36, s36, 0x20000
	s_addc_u32 s37, s37, 0
	s_mov_b32 m0, s38
	ds_read_b128 v[194:197], v162 offset:32768
	ds_read_b128 v[198:201], v162 offset:33792
	ds_read_b128 v[202:205], v162 offset:34816
	ds_read_b128 v[206:209], v162 offset:35840
	ds_read_b128 v[210:213], v162 offset:36864
	ds_read_b128 v[214:217], v162 offset:37888
	ds_read_b128 v[218:221], v162 offset:38912
	ds_read_b128 v[222:225], v162 offset:39936
	global_load_lds_dwordx4 v128, s[36:37]
	s_mov_b32 m0, s39
	s_nop 0
	global_load_lds_dwordx4 v132, s[36:37]
	s_waitcnt vmcnt(8)
	s_waitcnt lgkmcnt(0)
	s_barrier
	s_waitcnt lgkmcnt(0)
	v_mfma_f32_16x16x32_bf16 v[124:127], v[148:151], v[194:197], v[124:127]
	v_mfma_f32_16x16x32_bf16 v[120:123], v[166:169], v[194:197], v[120:123]
	v_mfma_f32_16x16x32_bf16 v[108:111], v[148:151], v[202:205], v[108:111]
	v_mfma_f32_16x16x32_bf16 v[104:107], v[166:169], v[202:205], v[104:107]
	v_mfma_f32_16x16x32_bf16 v[92:95], v[148:151], v[210:213], v[92:95]
	v_mfma_f32_16x16x32_bf16 v[88:91], v[166:169], v[210:213], v[88:91]
	v_mfma_f32_16x16x32_bf16 v[76:79], v[148:151], v[218:221], v[76:79]
	v_mfma_f32_16x16x32_bf16 v[72:75], v[166:169], v[218:221], v[72:75]
	v_mfma_f32_16x16x32_bf16 v[124:127], v[152:155], v[198:201], v[124:127]
	v_mfma_f32_16x16x32_bf16 v[120:123], v[170:173], v[198:201], v[120:123]
	v_mfma_f32_16x16x32_bf16 v[108:111], v[152:155], v[206:209], v[108:111]
	v_mfma_f32_16x16x32_bf16 v[104:107], v[170:173], v[206:209], v[104:107]
	v_mfma_f32_16x16x32_bf16 v[92:95], v[152:155], v[214:217], v[92:95]
	v_mfma_f32_16x16x32_bf16 v[88:91], v[170:173], v[214:217], v[88:91]
	v_mfma_f32_16x16x32_bf16 v[76:79], v[152:155], v[222:225], v[76:79]
	v_mfma_f32_16x16x32_bf16 v[72:75], v[170:173], v[222:225], v[72:75]
	v_mfma_f32_16x16x32_bf16 v[116:119], v[174:177], v[194:197], v[116:119]
	v_mfma_f32_16x16x32_bf16 v[112:115], v[182:185], v[194:197], v[112:115]
	v_mfma_f32_16x16x32_bf16 v[100:103], v[174:177], v[202:205], v[100:103]
	v_mfma_f32_16x16x32_bf16 v[96:99], v[182:185], v[202:205], v[96:99]
	v_mfma_f32_16x16x32_bf16 v[84:87], v[174:177], v[210:213], v[84:87]
	v_mfma_f32_16x16x32_bf16 v[80:83], v[182:185], v[210:213], v[80:83]
	v_mfma_f32_16x16x32_bf16 v[68:71], v[174:177], v[218:221], v[68:71]
	v_mfma_f32_16x16x32_bf16 v[64:67], v[182:185], v[218:221], v[64:67]
	v_mfma_f32_16x16x32_bf16 v[116:119], v[178:181], v[198:201], v[116:119]
	v_mfma_f32_16x16x32_bf16 v[112:115], v[190:193], v[198:201], v[112:115]
	v_mfma_f32_16x16x32_bf16 v[100:103], v[178:181], v[206:209], v[100:103]
	v_mfma_f32_16x16x32_bf16 v[96:99], v[190:193], v[206:209], v[96:99]
	v_mfma_f32_16x16x32_bf16 v[84:87], v[178:181], v[214:217], v[84:87]
	v_mfma_f32_16x16x32_bf16 v[80:83], v[190:193], v[214:217], v[80:83]
	v_mfma_f32_16x16x32_bf16 v[68:71], v[178:181], v[222:225], v[68:71]
	v_mfma_f32_16x16x32_bf16 v[64:67], v[190:193], v[222:225], v[64:67]
	s_barrier
	s_add_u32 s98, s34, 0x80
	s_addc_u32 s99, s35, 0
	s_add_u32 s100, s36, 0xfffe0080
	s_addc_u32 s101, s37, -1
	s_add_i32 s36, s52, s24
	s_mov_b32 m0, s36
	ds_read_b128 v[194:197], v162 offset:49152
	ds_read_b128 v[198:201], v162 offset:50176
	ds_read_b128 v[202:205], v162 offset:51200
	ds_read_b128 v[206:209], v162 offset:52224
	ds_read_b128 v[210:213], v162 offset:53248
	ds_read_b128 v[214:217], v162 offset:54272
	ds_read_b128 v[218:221], v162 offset:55296
	ds_read_b128 v[222:225], v162 offset:56320
	global_load_lds_dwordx4 v130, s[98:99]
	s_add_i32 m0, s36, 0x2000
	s_add_u32 s34, s34, 0x20080
	s_addc_u32 s35, s35, 0
	s_add_i32 s36, s53, s24
	global_load_lds_dwordx4 v134, s[98:99]
	s_mov_b32 m0, s36
	s_nop 0
	global_load_lds_dwordx4 v130, s[34:35]
	s_add_i32 m0, s36, 0x2000
	s_nop 0
	global_load_lds_dwordx4 v134, s[34:35]
	s_mov_b32 m0, s41
	s_nop 0
	global_load_lds_dwordx4 v128, s[100:101]
	s_mov_b32 m0, s42
	s_nop 0
	global_load_lds_dwordx4 v132, s[100:101]
	s_waitcnt vmcnt(8)
	s_waitcnt lgkmcnt(0)
	s_barrier
	s_waitcnt lgkmcnt(0)
	v_mfma_f32_16x16x32_bf16 v[60:63], v[148:151], v[194:197], v[60:63]
	v_mfma_f32_16x16x32_bf16 v[56:59], v[166:169], v[194:197], v[56:59]
	v_mfma_f32_16x16x32_bf16 v[44:47], v[148:151], v[202:205], v[44:47]
	v_mfma_f32_16x16x32_bf16 v[40:43], v[166:169], v[202:205], v[40:43]
	v_mfma_f32_16x16x32_bf16 v[28:31], v[148:151], v[210:213], v[28:31]
	v_mfma_f32_16x16x32_bf16 v[24:27], v[166:169], v[210:213], v[24:27]
	v_mfma_f32_16x16x32_bf16 v[12:15], v[148:151], v[218:221], v[12:15]
	v_mfma_f32_16x16x32_bf16 v[8:11], v[166:169], v[218:221], v[8:11]
	v_mfma_f32_16x16x32_bf16 v[60:63], v[152:155], v[198:201], v[60:63]
	v_mfma_f32_16x16x32_bf16 v[56:59], v[170:173], v[198:201], v[56:59]
	v_mfma_f32_16x16x32_bf16 v[44:47], v[152:155], v[206:209], v[44:47]
	v_mfma_f32_16x16x32_bf16 v[40:43], v[170:173], v[206:209], v[40:43]
	v_mfma_f32_16x16x32_bf16 v[28:31], v[152:155], v[214:217], v[28:31]
	v_mfma_f32_16x16x32_bf16 v[24:27], v[170:173], v[214:217], v[24:27]
	v_mfma_f32_16x16x32_bf16 v[12:15], v[152:155], v[222:225], v[12:15]
	v_mfma_f32_16x16x32_bf16 v[8:11], v[170:173], v[222:225], v[8:11]
	v_mfma_f32_16x16x32_bf16 v[52:55], v[174:177], v[194:197], v[52:55]
	v_mfma_f32_16x16x32_bf16 v[48:51], v[182:185], v[194:197], v[48:51]
	v_mfma_f32_16x16x32_bf16 v[36:39], v[174:177], v[202:205], v[36:39]
	v_mfma_f32_16x16x32_bf16 v[32:35], v[182:185], v[202:205], v[32:35]
	v_mfma_f32_16x16x32_bf16 v[20:23], v[174:177], v[210:213], v[20:23]
	v_mfma_f32_16x16x32_bf16 v[16:19], v[182:185], v[210:213], v[16:19]
	v_mfma_f32_16x16x32_bf16 v[4:7], v[174:177], v[218:221], v[4:7]
	v_mfma_f32_16x16x32_bf16 v[0:3], v[182:185], v[218:221], v[0:3]
	v_mfma_f32_16x16x32_bf16 v[52:55], v[178:181], v[198:201], v[52:55]
	v_mfma_f32_16x16x32_bf16 v[48:51], v[190:193], v[198:201], v[48:51]
	v_mfma_f32_16x16x32_bf16 v[36:39], v[178:181], v[206:209], v[36:39]
	v_mfma_f32_16x16x32_bf16 v[32:35], v[190:193], v[206:209], v[32:35]
	v_mfma_f32_16x16x32_bf16 v[20:23], v[178:181], v[214:217], v[20:23]
	v_mfma_f32_16x16x32_bf16 v[16:19], v[190:193], v[214:217], v[16:19]
	v_mfma_f32_16x16x32_bf16 v[4:7], v[178:181], v[222:225], v[4:7]
	v_mfma_f32_16x16x32_bf16 v[0:3], v[190:193], v[222:225], v[0:3]
	s_barrier
	s_add_i32 s51, s51, 2
	s_add_u32 s10, s10, 0x100
	s_addc_u32 s11, s11, 0
	s_add_u32 s49, s49, 0x100
	s_addc_u32 s50, s50, 0
	s_cmp_gt_u32 s51, 5
	s_cbranch_scc0 .LBB0_1037
	s_and_b64 vcc, exec, s[18:19]
	s_cbranch_vccz .LBB0_1040
	s_barrier

.LBB0_1452:
	ds_read_b128 v[128:131], v177
	ds_read_b128 v[132:135], v177 offset:1024
	ds_read_b128 v[136:139], v177 offset:2048
	ds_read_b128 v[140:143], v177 offset:3072
	ds_read_b128 v[160:163], v178
	ds_read_b128 v[164:167], v178 offset:1024
	ds_read_b128 v[168:171], v178 offset:2048
	ds_read_b128 v[182:185], v178 offset:3072
	s_add_u32 s28, s26, 0xfff80080
	s_addc_u32 s29, s27, -1
	s_cmp_eq_u32 s50, 28
	s_cselect_b32 s31, s15, s29
	s_cselect_b32 s30, s23, s28
	s_cselect_b32 s29, s17, s49
	s_cselect_b32 s28, s25, s48
	s_add_i32 m0, s34, 0xc000
	ds_read_b128 v[190:193], v179
	ds_read_b128 v[194:197], v179 offset:1024
	ds_read_b128 v[198:201], v179 offset:2048
	ds_read_b128 v[202:205], v179 offset:3072
	ds_read_b128 v[206:209], v179 offset:4096
	ds_read_b128 v[210:213], v179 offset:5120
	ds_read_b128 v[214:217], v179 offset:6144
	ds_read_b128 v[218:221], v179 offset:7168
	global_load_lds_dwordx4 v152, s[26:27]
	s_add_i32 m0, s34, 0xe000
	s_nop 0
	global_load_lds_dwordx4 v154, s[26:27]
	s_waitcnt vmcnt(8)
	s_waitcnt lgkmcnt(0)
	s_barrier
	s_waitcnt lgkmcnt(0)
	v_mfma_f32_16x16x32_bf16 v[124:127], v[128:131], v[190:193], v[124:127]
	v_mfma_f32_16x16x32_bf16 v[120:123], v[136:139], v[190:193], v[120:123]
	v_mfma_f32_16x16x32_bf16 v[108:111], v[128:131], v[198:201], v[108:111]
	v_mfma_f32_16x16x32_bf16 v[104:107], v[136:139], v[198:201], v[104:107]
	v_mfma_f32_16x16x32_bf16 v[92:95], v[128:131], v[206:209], v[92:95]
	v_mfma_f32_16x16x32_bf16 v[88:91], v[136:139], v[206:209], v[88:91]
	v_mfma_f32_16x16x32_bf16 v[76:79], v[128:131], v[214:217], v[76:79]
	v_mfma_f32_16x16x32_bf16 v[72:75], v[136:139], v[214:217], v[72:75]
	v_mfma_f32_16x16x32_bf16 v[124:127], v[132:135], v[194:197], v[124:127]
	v_mfma_f32_16x16x32_bf16 v[120:123], v[140:143], v[194:197], v[120:123]
	v_mfma_f32_16x16x32_bf16 v[108:111], v[132:135], v[202:205], v[108:111]
	v_mfma_f32_16x16x32_bf16 v[104:107], v[140:143], v[202:205], v[104:107]
	v_mfma_f32_16x16x32_bf16 v[92:95], v[132:135], v[210:213], v[92:95]
	v_mfma_f32_16x16x32_bf16 v[88:91], v[140:143], v[210:213], v[88:91]
	v_mfma_f32_16x16x32_bf16 v[76:79], v[132:135], v[218:221], v[76:79]
	v_mfma_f32_16x16x32_bf16 v[72:75], v[140:143], v[218:221], v[72:75]
	v_mfma_f32_16x16x32_bf16 v[116:119], v[160:163], v[190:193], v[116:119]
	v_mfma_f32_16x16x32_bf16 v[112:115], v[168:171], v[190:193], v[112:115]
	v_mfma_f32_16x16x32_bf16 v[100:103], v[160:163], v[198:201], v[100:103]
	v_mfma_f32_16x16x32_bf16 v[96:99], v[168:171], v[198:201], v[96:99]
	v_mfma_f32_16x16x32_bf16 v[84:87], v[160:163], v[206:209], v[84:87]
	v_mfma_f32_16x16x32_bf16 v[80:83], v[168:171], v[206:209], v[80:83]
	v_mfma_f32_16x16x32_bf16 v[68:71], v[160:163], v[214:217], v[68:71]
	v_mfma_f32_16x16x32_bf16 v[64:67], v[168:171], v[214:217], v[64:67]
	v_mfma_f32_16x16x32_bf16 v[116:119], v[164:167], v[194:197], v[116:119]
	v_mfma_f32_16x16x32_bf16 v[112:115], v[182:185], v[194:197], v[112:115]
	v_mfma_f32_16x16x32_bf16 v[100:103], v[164:167], v[202:205], v[100:103]
	v_mfma_f32_16x16x32_bf16 v[96:99], v[182:185], v[202:205], v[96:99]
	v_mfma_f32_16x16x32_bf16 v[84:87], v[164:167], v[210:213], v[84:87]
	v_mfma_f32_16x16x32_bf16 v[80:83], v[182:185], v[210:213], v[80:83]
	v_mfma_f32_16x16x32_bf16 v[68:71], v[164:167], v[218:221], v[68:71]
	v_mfma_f32_16x16x32_bf16 v[64:67], v[182:185], v[218:221], v[64:67]
	s_barrier
	s_add_i32 s51, s45, s33
	s_mov_b32 m0, s51
	ds_read_b128 v[190:193], v179 offset:16384
	ds_read_b128 v[194:197], v179 offset:17408
	ds_read_b128 v[198:201], v179 offset:18432
	ds_read_b128 v[202:205], v179 offset:19456
	ds_read_b128 v[206:209], v179 offset:20480
	ds_read_b128 v[210:213], v179 offset:21504
	ds_read_b128 v[214:217], v179 offset:22528
	ds_read_b128 v[218:221], v179 offset:23552
	global_load_lds_dwordx4 v146, s[28:29]
	s_add_i32 m0, s51, 0x2000
	s_add_u32 s52, s28, 0x80000
	s_addc_u32 s53, s29, 0
	s_add_i32 s51, s46, s33
	global_load_lds_dwordx4 v150, s[28:29]
	s_mov_b32 m0, s51
	s_nop 0
	global_load_lds_dwordx4 v146, s[52:53]
	s_add_i32 m0, s51, 0x2000
	s_nop 0
	global_load_lds_dwordx4 v150, s[52:53]
	s_mov_b32 m0, s34
	s_nop 0
	global_load_lds_dwordx4 v144, s[30:31]
	s_mov_b32 m0, s35
	s_nop 0
	global_load_lds_dwordx4 v148, s[30:31]
	s_waitcnt vmcnt(8)
	s_waitcnt lgkmcnt(0)
	s_barrier
	s_waitcnt lgkmcnt(0)
	v_mfma_f32_16x16x32_bf16 v[60:63], v[128:131], v[190:193], v[60:63]
	v_mfma_f32_16x16x32_bf16 v[56:59], v[136:139], v[190:193], v[56:59]
	v_mfma_f32_16x16x32_bf16 v[44:47], v[128:131], v[198:201], v[44:47]
	v_mfma_f32_16x16x32_bf16 v[40:43], v[136:139], v[198:201], v[40:43]
	v_mfma_f32_16x16x32_bf16 v[28:31], v[128:131], v[206:209], v[28:31]
	v_mfma_f32_16x16x32_bf16 v[24:27], v[136:139], v[206:209], v[24:27]
	v_mfma_f32_16x16x32_bf16 v[12:15], v[128:131], v[214:217], v[12:15]
	v_mfma_f32_16x16x32_bf16 v[8:11], v[136:139], v[214:217], v[8:11]
	v_mfma_f32_16x16x32_bf16 v[60:63], v[132:135], v[194:197], v[60:63]
	v_mfma_f32_16x16x32_bf16 v[56:59], v[140:143], v[194:197], v[56:59]
	v_mfma_f32_16x16x32_bf16 v[44:47], v[132:135], v[202:205], v[44:47]
	v_mfma_f32_16x16x32_bf16 v[40:43], v[140:143], v[202:205], v[40:43]
	v_mfma_f32_16x16x32_bf16 v[28:31], v[132:135], v[210:213], v[28:31]
	v_mfma_f32_16x16x32_bf16 v[24:27], v[140:143], v[210:213], v[24:27]
	v_mfma_f32_16x16x32_bf16 v[12:15], v[132:135], v[218:221], v[12:15]
	v_mfma_f32_16x16x32_bf16 v[8:11], v[140:143], v[218:221], v[8:11]
	v_mfma_f32_16x16x32_bf16 v[52:55], v[160:163], v[190:193], v[52:55]
	v_mfma_f32_16x16x32_bf16 v[48:51], v[168:171], v[190:193], v[48:51]
	v_mfma_f32_16x16x32_bf16 v[36:39], v[160:163], v[198:201], v[36:39]
	v_mfma_f32_16x16x32_bf16 v[32:35], v[168:171], v[198:201], v[32:35]
	v_mfma_f32_16x16x32_bf16 v[20:23], v[160:163], v[206:209], v[20:23]
	v_mfma_f32_16x16x32_bf16 v[16:19], v[168:171], v[206:209], v[16:19]
	v_mfma_f32_16x16x32_bf16 v[4:7], v[160:163], v[214:217], v[4:7]
	v_mfma_f32_16x16x32_bf16 v[0:3], v[168:171], v[214:217], v[0:3]
	v_mfma_f32_16x16x32_bf16 v[52:55], v[164:167], v[194:197], v[52:55]
	v_mfma_f32_16x16x32_bf16 v[48:51], v[182:185], v[194:197], v[48:51]
	v_mfma_f32_16x16x32_bf16 v[36:39], v[164:167], v[202:205], v[36:39]
	v_mfma_f32_16x16x32_bf16 v[32:35], v[182:185], v[202:205], v[32:35]
	v_mfma_f32_16x16x32_bf16 v[20:23], v[164:167], v[210:213], v[20:23]
	v_mfma_f32_16x16x32_bf16 v[16:19], v[182:185], v[210:213], v[16:19]
	v_mfma_f32_16x16x32_bf16 v[4:7], v[164:167], v[218:221], v[4:7]
	v_mfma_f32_16x16x32_bf16 v[0:3], v[182:185], v[218:221], v[0:3]
	s_barrier
	s_add_i32 s51, 0, 0x18000
	s_add_i32 s52, 0, 0x1c000
	v_add_u32_e32 v140, s51, v175
	v_add_u32_e32 v181, s52, v175
	ds_read_b128 v[128:131], v140
	ds_read_b128 v[132:135], v140 offset:1024
	ds_read_b128 v[136:139], v140 offset:2048
	ds_read_b128 v[140:143], v140 offset:3072
	ds_read_b128 v[160:163], v181
	ds_read_b128 v[164:167], v181 offset:1024
	ds_read_b128 v[168:171], v181 offset:2048
	ds_read_b128 v[182:185], v181 offset:3072
	s_add_u32 s30, s30, 0x80000
	s_addc_u32 s31, s31, 0
	s_mov_b32 m0, s36
	ds_read_b128 v[190:193], v179 offset:32768
	ds_read_b128 v[194:197], v179 offset:33792
	ds_read_b128 v[198:201], v179 offset:34816
	ds_read_b128 v[202:205], v179 offset:35840
	ds_read_b128 v[206:209], v179 offset:36864
	ds_read_b128 v[210:213], v179 offset:37888
	ds_read_b128 v[214:217], v179 offset:38912
	ds_read_b128 v[218:221], v179 offset:39936
	global_load_lds_dwordx4 v144, s[30:31]
	s_mov_b32 m0, s37
	s_nop 0
	global_load_lds_dwordx4 v148, s[30:31]
	s_waitcnt vmcnt(8)
	s_waitcnt lgkmcnt(0)
	s_barrier
	s_waitcnt lgkmcnt(0)
	v_mfma_f32_16x16x32_bf16 v[124:127], v[128:131], v[190:193], v[124:127]
	v_mfma_f32_16x16x32_bf16 v[120:123], v[136:139], v[190:193], v[120:123]
	v_mfma_f32_16x16x32_bf16 v[108:111], v[128:131], v[198:201], v[108:111]
	v_mfma_f32_16x16x32_bf16 v[104:107], v[136:139], v[198:201], v[104:107]
	v_mfma_f32_16x16x32_bf16 v[92:95], v[128:131], v[206:209], v[92:95]
	v_mfma_f32_16x16x32_bf16 v[88:91], v[136:139], v[206:209], v[88:91]
	v_mfma_f32_16x16x32_bf16 v[76:79], v[128:131], v[214:217], v[76:79]
	v_mfma_f32_16x16x32_bf16 v[72:75], v[136:139], v[214:217], v[72:75]
	v_mfma_f32_16x16x32_bf16 v[124:127], v[132:135], v[194:197], v[124:127]
	v_mfma_f32_16x16x32_bf16 v[120:123], v[140:143], v[194:197], v[120:123]
	v_mfma_f32_16x16x32_bf16 v[108:111], v[132:135], v[202:205], v[108:111]
	v_mfma_f32_16x16x32_bf16 v[104:107], v[140:143], v[202:205], v[104:107]
	v_mfma_f32_16x16x32_bf16 v[92:95], v[132:135], v[210:213], v[92:95]
	v_mfma_f32_16x16x32_bf16 v[88:91], v[140:143], v[210:213], v[88:91]
	v_mfma_f32_16x16x32_bf16 v[76:79], v[132:135], v[218:221], v[76:79]
	v_mfma_f32_16x16x32_bf16 v[72:75], v[140:143], v[218:221], v[72:75]
	v_mfma_f32_16x16x32_bf16 v[116:119], v[160:163], v[190:193], v[116:119]
	v_mfma_f32_16x16x32_bf16 v[112:115], v[168:171], v[190:193], v[112:115]
	v_mfma_f32_16x16x32_bf16 v[100:103], v[160:163], v[198:201], v[100:103]
	v_mfma_f32_16x16x32_bf16 v[96:99], v[168:171], v[198:201], v[96:99]
	v_mfma_f32_16x16x32_bf16 v[84:87], v[160:163], v[206:209], v[84:87]
	v_mfma_f32_16x16x32_bf16 v[80:83], v[168:171], v[206:209], v[80:83]
	v_mfma_f32_16x16x32_bf16 v[68:71], v[160:163], v[214:217], v[68:71]
	v_mfma_f32_16x16x32_bf16 v[64:67], v[168:171], v[214:217], v[64:67]
	v_mfma_f32_16x16x32_bf16 v[116:119], v[164:167], v[194:197], v[116:119]
	v_mfma_f32_16x16x32_bf16 v[112:115], v[182:185], v[194:197], v[112:115]
	v_mfma_f32_16x16x32_bf16 v[100:103], v[164:167], v[202:205], v[100:103]
	v_mfma_f32_16x16x32_bf16 v[96:99], v[182:185], v[202:205], v[96:99]
	v_mfma_f32_16x16x32_bf16 v[84:87], v[164:167], v[210:213], v[84:87]
	v_mfma_f32_16x16x32_bf16 v[80:83], v[182:185], v[210:213], v[80:83]
	v_mfma_f32_16x16x32_bf16 v[68:71], v[164:167], v[218:221], v[68:71]
	v_mfma_f32_16x16x32_bf16 v[64:67], v[182:185], v[218:221], v[64:67]
	s_barrier
	s_add_u32 s98, s28, 0x80
	s_addc_u32 s99, s29, 0
	s_add_u32 s100, s30, 0xfff80080
	s_addc_u32 s101, s31, -1
	s_add_i32 s30, s51, s33
	s_mov_b32 m0, s30
	ds_read_b128 v[190:193], v179 offset:49152
	ds_read_b128 v[194:197], v179 offset:50176
	ds_read_b128 v[198:201], v179 offset:51200
	ds_read_b128 v[202:205], v179 offset:52224
	ds_read_b128 v[206:209], v179 offset:53248
	ds_read_b128 v[210:213], v179 offset:54272
	ds_read_b128 v[214:217], v179 offset:55296
	ds_read_b128 v[218:221], v179 offset:56320
	global_load_lds_dwordx4 v146, s[98:99]
	s_add_i32 m0, s30, 0x2000
	s_add_u32 s28, s28, 0x80080
	s_addc_u32 s29, s29, 0
	s_add_i32 s30, s52, s33
	global_load_lds_dwordx4 v150, s[98:99]
	s_mov_b32 m0, s30
	s_nop 0
	global_load_lds_dwordx4 v146, s[28:29]
	s_add_i32 m0, s30, 0x2000
	s_nop 0
	global_load_lds_dwordx4 v150, s[28:29]
	s_mov_b32 m0, s41
	s_nop 0
	global_load_lds_dwordx4 v144, s[100:101]
	s_mov_b32 m0, s42
	s_nop 0
	global_load_lds_dwordx4 v148, s[100:101]
	s_waitcnt vmcnt(8)
	s_waitcnt lgkmcnt(0)
	s_barrier
	s_waitcnt lgkmcnt(0)
	v_mfma_f32_16x16x32_bf16 v[60:63], v[128:131], v[190:193], v[60:63]
	v_mfma_f32_16x16x32_bf16 v[56:59], v[136:139], v[190:193], v[56:59]
	v_mfma_f32_16x16x32_bf16 v[44:47], v[128:131], v[198:201], v[44:47]
	v_mfma_f32_16x16x32_bf16 v[40:43], v[136:139], v[198:201], v[40:43]
	v_mfma_f32_16x16x32_bf16 v[28:31], v[128:131], v[206:209], v[28:31]
	v_mfma_f32_16x16x32_bf16 v[24:27], v[136:139], v[206:209], v[24:27]
	v_mfma_f32_16x16x32_bf16 v[12:15], v[128:131], v[214:217], v[12:15]
	v_mfma_f32_16x16x32_bf16 v[8:11], v[136:139], v[214:217], v[8:11]
	v_mfma_f32_16x16x32_bf16 v[60:63], v[132:135], v[194:197], v[60:63]
	v_mfma_f32_16x16x32_bf16 v[56:59], v[140:143], v[194:197], v[56:59]
	v_mfma_f32_16x16x32_bf16 v[44:47], v[132:135], v[202:205], v[44:47]
	v_mfma_f32_16x16x32_bf16 v[40:43], v[140:143], v[202:205], v[40:43]
	v_mfma_f32_16x16x32_bf16 v[28:31], v[132:135], v[210:213], v[28:31]
	v_mfma_f32_16x16x32_bf16 v[24:27], v[140:143], v[210:213], v[24:27]
	v_mfma_f32_16x16x32_bf16 v[12:15], v[132:135], v[218:221], v[12:15]
	v_mfma_f32_16x16x32_bf16 v[8:11], v[140:143], v[218:221], v[8:11]
	v_mfma_f32_16x16x32_bf16 v[52:55], v[160:163], v[190:193], v[52:55]
	v_mfma_f32_16x16x32_bf16 v[48:51], v[168:171], v[190:193], v[48:51]
	v_mfma_f32_16x16x32_bf16 v[36:39], v[160:163], v[198:201], v[36:39]
	v_mfma_f32_16x16x32_bf16 v[32:35], v[168:171], v[198:201], v[32:35]
	v_mfma_f32_16x16x32_bf16 v[20:23], v[160:163], v[206:209], v[20:23]
	v_mfma_f32_16x16x32_bf16 v[16:19], v[168:171], v[206:209], v[16:19]
	v_mfma_f32_16x16x32_bf16 v[4:7], v[160:163], v[214:217], v[4:7]
	v_mfma_f32_16x16x32_bf16 v[0:3], v[168:171], v[214:217], v[0:3]
	v_mfma_f32_16x16x32_bf16 v[52:55], v[164:167], v[194:197], v[52:55]
	v_mfma_f32_16x16x32_bf16 v[48:51], v[182:185], v[194:197], v[48:51]
	v_mfma_f32_16x16x32_bf16 v[36:39], v[164:167], v[202:205], v[36:39]
	v_mfma_f32_16x16x32_bf16 v[32:35], v[182:185], v[202:205], v[32:35]
	v_mfma_f32_16x16x32_bf16 v[20:23], v[164:167], v[210:213], v[20:23]
	v_mfma_f32_16x16x32_bf16 v[16:19], v[182:185], v[210:213], v[16:19]
	v_mfma_f32_16x16x32_bf16 v[4:7], v[164:167], v[218:221], v[4:7]
	v_mfma_f32_16x16x32_bf16 v[0:3], v[182:185], v[218:221], v[0:3]
	s_barrier
	s_add_i32 s50, s50, 2
	s_add_u32 s26, s26, 0x100
	s_addc_u32 s27, s27, 0
	s_add_u32 s48, s48, 0x100
	s_addc_u32 s49, s49, 0
	s_cmp_gt_u32 s50, 29
	s_cbranch_scc0 .LBB0_1452
	s_and_b64 vcc, exec, s[10:11]
	s_cbranch_vccz .LBB0_1455
	s_barrier

.LBB0_1539:
	ds_read_b128 v[156:159], v151
	ds_read_b128 v[160:163], v151 offset:1024
	ds_read_b128 v[164:167], v151 offset:2048
	ds_read_b128 v[168:171], v151 offset:3072
	ds_read_b128 v[172:175], v152
	ds_read_b128 v[176:179], v152 offset:1024
	ds_read_b128 v[180:183], v152 offset:2048
	ds_read_b128 v[184:187], v152 offset:3072
	s_add_u32 s22, s20, 0xfff80080
	s_addc_u32 s23, s21, -1
	s_cmp_eq_u32 s48, 28
	s_cselect_b32 s25, s11, s23
	s_cselect_b32 s24, s44, s22
	s_cselect_b32 s23, s13, s47
	s_cselect_b32 s22, s45, s46
	s_add_i32 m0, s19, 0xc000
	ds_read_b128 v[190:193], v153
	ds_read_b128 v[194:197], v153 offset:1024
	ds_read_b128 v[198:201], v153 offset:2048
	ds_read_b128 v[202:205], v153 offset:3072
	ds_read_b128 v[206:209], v153 offset:4096
	ds_read_b128 v[210:213], v153 offset:5120
	ds_read_b128 v[214:217], v153 offset:6144
	ds_read_b128 v[218:221], v153 offset:7168
	global_load_lds_dwordx4 v138, s[20:21]
	s_add_i32 m0, s19, 0xe000
	s_nop 0
	global_load_lds_dwordx4 v140, s[20:21]
	s_waitcnt vmcnt(8)
	s_waitcnt lgkmcnt(0)
	s_barrier
	s_waitcnt lgkmcnt(0)
	v_mfma_f32_16x16x32_bf16 v[116:119], v[156:159], v[190:193], v[116:119]
	v_mfma_f32_16x16x32_bf16 v[112:115], v[164:167], v[190:193], v[112:115]
	v_mfma_f32_16x16x32_bf16 v[100:103], v[156:159], v[198:201], v[100:103]
	v_mfma_f32_16x16x32_bf16 v[96:99], v[164:167], v[198:201], v[96:99]
	v_mfma_f32_16x16x32_bf16 v[84:87], v[156:159], v[206:209], v[84:87]
	v_mfma_f32_16x16x32_bf16 v[80:83], v[164:167], v[206:209], v[80:83]
	v_mfma_f32_16x16x32_bf16 v[68:71], v[156:159], v[214:217], v[68:71]
	v_mfma_f32_16x16x32_bf16 v[64:67], v[164:167], v[214:217], v[64:67]
	v_mfma_f32_16x16x32_bf16 v[116:119], v[160:163], v[194:197], v[116:119]
	v_mfma_f32_16x16x32_bf16 v[112:115], v[168:171], v[194:197], v[112:115]
	v_mfma_f32_16x16x32_bf16 v[100:103], v[160:163], v[202:205], v[100:103]
	v_mfma_f32_16x16x32_bf16 v[96:99], v[168:171], v[202:205], v[96:99]
	v_mfma_f32_16x16x32_bf16 v[84:87], v[160:163], v[210:213], v[84:87]
	v_mfma_f32_16x16x32_bf16 v[80:83], v[168:171], v[210:213], v[80:83]
	v_mfma_f32_16x16x32_bf16 v[68:71], v[160:163], v[218:221], v[68:71]
	v_mfma_f32_16x16x32_bf16 v[64:67], v[168:171], v[218:221], v[64:67]
	v_mfma_f32_16x16x32_bf16 v[124:127], v[172:175], v[190:193], v[124:127]
	v_mfma_f32_16x16x32_bf16 v[120:123], v[180:183], v[190:193], v[120:123]
	v_mfma_f32_16x16x32_bf16 v[108:111], v[172:175], v[198:201], v[108:111]
	v_mfma_f32_16x16x32_bf16 v[104:107], v[180:183], v[198:201], v[104:107]
	v_mfma_f32_16x16x32_bf16 v[92:95], v[172:175], v[206:209], v[92:95]
	v_mfma_f32_16x16x32_bf16 v[88:91], v[180:183], v[206:209], v[88:91]
	v_mfma_f32_16x16x32_bf16 v[76:79], v[172:175], v[214:217], v[76:79]
	v_mfma_f32_16x16x32_bf16 v[72:75], v[180:183], v[214:217], v[72:75]
	v_mfma_f32_16x16x32_bf16 v[124:127], v[176:179], v[194:197], v[124:127]
	v_mfma_f32_16x16x32_bf16 v[120:123], v[184:187], v[194:197], v[120:123]
	v_mfma_f32_16x16x32_bf16 v[108:111], v[176:179], v[202:205], v[108:111]
	v_mfma_f32_16x16x32_bf16 v[104:107], v[184:187], v[202:205], v[104:107]
	v_mfma_f32_16x16x32_bf16 v[92:95], v[176:179], v[210:213], v[92:95]
	v_mfma_f32_16x16x32_bf16 v[88:91], v[184:187], v[210:213], v[88:91]
	v_mfma_f32_16x16x32_bf16 v[76:79], v[176:179], v[218:221], v[76:79]
	v_mfma_f32_16x16x32_bf16 v[72:75], v[184:187], v[218:221], v[72:75]
	s_barrier
	s_add_i32 s49, s40, s28
	s_mov_b32 m0, s49
	ds_read_b128 v[190:193], v153 offset:16384
	ds_read_b128 v[194:197], v153 offset:17408
	ds_read_b128 v[198:201], v153 offset:18432
	ds_read_b128 v[202:205], v153 offset:19456
	ds_read_b128 v[206:209], v153 offset:20480
	ds_read_b128 v[210:213], v153 offset:21504
	ds_read_b128 v[214:217], v153 offset:22528
	ds_read_b128 v[218:221], v153 offset:23552
	global_load_lds_dwordx4 v132, s[22:23]
	s_add_i32 m0, s49, 0x2000
	s_add_u32 s50, s22, 0x80000
	s_addc_u32 s51, s23, 0
	s_add_i32 s49, s41, s28
	global_load_lds_dwordx4 v128, s[22:23]
	s_mov_b32 m0, s49
	s_nop 0
	global_load_lds_dwordx4 v132, s[50:51]
	s_add_i32 m0, s49, 0x2000
	s_nop 0
	global_load_lds_dwordx4 v128, s[50:51]
	s_mov_b32 m0, s19
	s_nop 0
	global_load_lds_dwordx4 v134, s[24:25]
	s_mov_b32 m0, s30
	s_nop 0
	global_load_lds_dwordx4 v130, s[24:25]
	s_waitcnt vmcnt(8)
	s_waitcnt lgkmcnt(0)
	s_barrier
	s_waitcnt lgkmcnt(0)
	v_mfma_f32_16x16x32_bf16 v[52:55], v[156:159], v[190:193], v[52:55]
	v_mfma_f32_16x16x32_bf16 v[48:51], v[164:167], v[190:193], v[48:51]
	v_mfma_f32_16x16x32_bf16 v[36:39], v[156:159], v[198:201], v[36:39]
	v_mfma_f32_16x16x32_bf16 v[32:35], v[164:167], v[198:201], v[32:35]
	v_mfma_f32_16x16x32_bf16 v[20:23], v[156:159], v[206:209], v[20:23]
	v_mfma_f32_16x16x32_bf16 v[16:19], v[164:167], v[206:209], v[16:19]
	v_mfma_f32_16x16x32_bf16 v[8:11], v[156:159], v[214:217], v[8:11]
	v_mfma_f32_16x16x32_bf16 v[0:3], v[164:167], v[214:217], v[0:3]
	v_mfma_f32_16x16x32_bf16 v[52:55], v[160:163], v[194:197], v[52:55]
	v_mfma_f32_16x16x32_bf16 v[48:51], v[168:171], v[194:197], v[48:51]
	v_mfma_f32_16x16x32_bf16 v[36:39], v[160:163], v[202:205], v[36:39]
	v_mfma_f32_16x16x32_bf16 v[32:35], v[168:171], v[202:205], v[32:35]
	v_mfma_f32_16x16x32_bf16 v[20:23], v[160:163], v[210:213], v[20:23]
	v_mfma_f32_16x16x32_bf16 v[16:19], v[168:171], v[210:213], v[16:19]
	v_mfma_f32_16x16x32_bf16 v[8:11], v[160:163], v[218:221], v[8:11]
	v_mfma_f32_16x16x32_bf16 v[0:3], v[168:171], v[218:221], v[0:3]
	v_mfma_f32_16x16x32_bf16 v[60:63], v[172:175], v[190:193], v[60:63]
	v_mfma_f32_16x16x32_bf16 v[56:59], v[180:183], v[190:193], v[56:59]
	v_mfma_f32_16x16x32_bf16 v[44:47], v[172:175], v[198:201], v[44:47]
	v_mfma_f32_16x16x32_bf16 v[40:43], v[180:183], v[198:201], v[40:43]
	v_mfma_f32_16x16x32_bf16 v[28:31], v[172:175], v[206:209], v[28:31]
	v_mfma_f32_16x16x32_bf16 v[24:27], v[180:183], v[206:209], v[24:27]
	v_mfma_f32_16x16x32_bf16 v[12:15], v[172:175], v[214:217], v[12:15]
	v_mfma_f32_16x16x32_bf16 v[4:7], v[180:183], v[214:217], v[4:7]
	v_mfma_f32_16x16x32_bf16 v[60:63], v[176:179], v[194:197], v[60:63]
	v_mfma_f32_16x16x32_bf16 v[56:59], v[184:187], v[194:197], v[56:59]
	v_mfma_f32_16x16x32_bf16 v[44:47], v[176:179], v[202:205], v[44:47]
	v_mfma_f32_16x16x32_bf16 v[40:43], v[184:187], v[202:205], v[40:43]
	v_mfma_f32_16x16x32_bf16 v[28:31], v[176:179], v[210:213], v[28:31]
	v_mfma_f32_16x16x32_bf16 v[24:27], v[184:187], v[210:213], v[24:27]
	v_mfma_f32_16x16x32_bf16 v[12:15], v[176:179], v[218:221], v[12:15]
	v_mfma_f32_16x16x32_bf16 v[4:7], v[184:187], v[218:221], v[4:7]
	s_barrier
	s_add_i32 s49, 0, 0x18000
	s_add_i32 s50, 0, 0x1c000
	v_add_u32_e32 v168, s49, v149
	v_add_u32_e32 v184, s50, v149
	ds_read_b128 v[156:159], v168
	ds_read_b128 v[160:163], v168 offset:1024
	ds_read_b128 v[164:167], v168 offset:2048
	ds_read_b128 v[168:171], v168 offset:3072
	ds_read_b128 v[172:175], v184
	ds_read_b128 v[176:179], v184 offset:1024
	ds_read_b128 v[180:183], v184 offset:2048
	ds_read_b128 v[184:187], v184 offset:3072
	s_add_u32 s24, s24, 0x80000
	s_addc_u32 s25, s25, 0
	s_mov_b32 m0, s31
	ds_read_b128 v[190:193], v153 offset:32768
	ds_read_b128 v[194:197], v153 offset:33792
	ds_read_b128 v[198:201], v153 offset:34816
	ds_read_b128 v[202:205], v153 offset:35840
	ds_read_b128 v[206:209], v153 offset:36864
	ds_read_b128 v[210:213], v153 offset:37888
	ds_read_b128 v[214:217], v153 offset:38912
	ds_read_b128 v[218:221], v153 offset:39936
	global_load_lds_dwordx4 v134, s[24:25]
	s_mov_b32 m0, s33
	s_nop 0
	global_load_lds_dwordx4 v130, s[24:25]
	s_waitcnt vmcnt(8)
	s_waitcnt lgkmcnt(0)
	s_barrier
	s_waitcnt lgkmcnt(0)
	v_mfma_f32_16x16x32_bf16 v[116:119], v[156:159], v[190:193], v[116:119]
	v_mfma_f32_16x16x32_bf16 v[112:115], v[164:167], v[190:193], v[112:115]
	v_mfma_f32_16x16x32_bf16 v[100:103], v[156:159], v[198:201], v[100:103]
	v_mfma_f32_16x16x32_bf16 v[96:99], v[164:167], v[198:201], v[96:99]
	v_mfma_f32_16x16x32_bf16 v[84:87], v[156:159], v[206:209], v[84:87]
	v_mfma_f32_16x16x32_bf16 v[80:83], v[164:167], v[206:209], v[80:83]
	v_mfma_f32_16x16x32_bf16 v[68:71], v[156:159], v[214:217], v[68:71]
	v_mfma_f32_16x16x32_bf16 v[64:67], v[164:167], v[214:217], v[64:67]
	v_mfma_f32_16x16x32_bf16 v[116:119], v[160:163], v[194:197], v[116:119]
	v_mfma_f32_16x16x32_bf16 v[112:115], v[168:171], v[194:197], v[112:115]
	v_mfma_f32_16x16x32_bf16 v[100:103], v[160:163], v[202:205], v[100:103]
	v_mfma_f32_16x16x32_bf16 v[96:99], v[168:171], v[202:205], v[96:99]
	v_mfma_f32_16x16x32_bf16 v[84:87], v[160:163], v[210:213], v[84:87]
	v_mfma_f32_16x16x32_bf16 v[80:83], v[168:171], v[210:213], v[80:83]
	v_mfma_f32_16x16x32_bf16 v[68:71], v[160:163], v[218:221], v[68:71]
	v_mfma_f32_16x16x32_bf16 v[64:67], v[168:171], v[218:221], v[64:67]
	v_mfma_f32_16x16x32_bf16 v[124:127], v[172:175], v[190:193], v[124:127]
	v_mfma_f32_16x16x32_bf16 v[120:123], v[180:183], v[190:193], v[120:123]
	v_mfma_f32_16x16x32_bf16 v[108:111], v[172:175], v[198:201], v[108:111]
	v_mfma_f32_16x16x32_bf16 v[104:107], v[180:183], v[198:201], v[104:107]
	v_mfma_f32_16x16x32_bf16 v[92:95], v[172:175], v[206:209], v[92:95]
	v_mfma_f32_16x16x32_bf16 v[88:91], v[180:183], v[206:209], v[88:91]
	v_mfma_f32_16x16x32_bf16 v[76:79], v[172:175], v[214:217], v[76:79]
	v_mfma_f32_16x16x32_bf16 v[72:75], v[180:183], v[214:217], v[72:75]
	v_mfma_f32_16x16x32_bf16 v[124:127], v[176:179], v[194:197], v[124:127]
	v_mfma_f32_16x16x32_bf16 v[120:123], v[184:187], v[194:197], v[120:123]
	v_mfma_f32_16x16x32_bf16 v[108:111], v[176:179], v[202:205], v[108:111]
	v_mfma_f32_16x16x32_bf16 v[104:107], v[184:187], v[202:205], v[104:107]
	v_mfma_f32_16x16x32_bf16 v[92:95], v[176:179], v[210:213], v[92:95]
	v_mfma_f32_16x16x32_bf16 v[88:91], v[184:187], v[210:213], v[88:91]
	v_mfma_f32_16x16x32_bf16 v[76:79], v[176:179], v[218:221], v[76:79]
	v_mfma_f32_16x16x32_bf16 v[72:75], v[184:187], v[218:221], v[72:75]
	s_barrier
	s_add_u32 s98, s22, 0x80
	s_addc_u32 s99, s23, 0
	s_add_u32 s100, s24, 0xfff80080
	s_addc_u32 s101, s25, -1
	s_add_i32 s24, s49, s28
	s_mov_b32 m0, s24
	ds_read_b128 v[190:193], v153 offset:49152
	ds_read_b128 v[194:197], v153 offset:50176
	ds_read_b128 v[198:201], v153 offset:51200
	ds_read_b128 v[202:205], v153 offset:52224
	ds_read_b128 v[206:209], v153 offset:53248
	ds_read_b128 v[210:213], v153 offset:54272
	ds_read_b128 v[214:217], v153 offset:55296
	ds_read_b128 v[218:221], v153 offset:56320
	global_load_lds_dwordx4 v132, s[98:99]
	s_add_i32 m0, s24, 0x2000
	s_add_u32 s22, s22, 0x80080
	s_addc_u32 s23, s23, 0
	s_add_i32 s24, s50, s28
	global_load_lds_dwordx4 v128, s[98:99]
	s_mov_b32 m0, s24
	s_nop 0
	global_load_lds_dwordx4 v132, s[22:23]
	s_add_i32 m0, s24, 0x2000
	s_nop 0
	global_load_lds_dwordx4 v128, s[22:23]
	s_mov_b32 m0, s36
	s_nop 0
	global_load_lds_dwordx4 v134, s[100:101]
	s_mov_b32 m0, s37
	s_nop 0
	global_load_lds_dwordx4 v130, s[100:101]
	s_waitcnt vmcnt(8)
	s_waitcnt lgkmcnt(0)
	s_barrier
	s_waitcnt lgkmcnt(0)
	v_mfma_f32_16x16x32_bf16 v[52:55], v[156:159], v[190:193], v[52:55]
	v_mfma_f32_16x16x32_bf16 v[48:51], v[164:167], v[190:193], v[48:51]
	v_mfma_f32_16x16x32_bf16 v[36:39], v[156:159], v[198:201], v[36:39]
	v_mfma_f32_16x16x32_bf16 v[32:35], v[164:167], v[198:201], v[32:35]
	v_mfma_f32_16x16x32_bf16 v[20:23], v[156:159], v[206:209], v[20:23]
	v_mfma_f32_16x16x32_bf16 v[16:19], v[164:167], v[206:209], v[16:19]
	v_mfma_f32_16x16x32_bf16 v[8:11], v[156:159], v[214:217], v[8:11]
	v_mfma_f32_16x16x32_bf16 v[0:3], v[164:167], v[214:217], v[0:3]
	v_mfma_f32_16x16x32_bf16 v[52:55], v[160:163], v[194:197], v[52:55]
	v_mfma_f32_16x16x32_bf16 v[48:51], v[168:171], v[194:197], v[48:51]
	v_mfma_f32_16x16x32_bf16 v[36:39], v[160:163], v[202:205], v[36:39]
	v_mfma_f32_16x16x32_bf16 v[32:35], v[168:171], v[202:205], v[32:35]
	v_mfma_f32_16x16x32_bf16 v[20:23], v[160:163], v[210:213], v[20:23]
	v_mfma_f32_16x16x32_bf16 v[16:19], v[168:171], v[210:213], v[16:19]
	v_mfma_f32_16x16x32_bf16 v[8:11], v[160:163], v[218:221], v[8:11]
	v_mfma_f32_16x16x32_bf16 v[0:3], v[168:171], v[218:221], v[0:3]
	v_mfma_f32_16x16x32_bf16 v[60:63], v[172:175], v[190:193], v[60:63]
	v_mfma_f32_16x16x32_bf16 v[56:59], v[180:183], v[190:193], v[56:59]
	v_mfma_f32_16x16x32_bf16 v[44:47], v[172:175], v[198:201], v[44:47]
	v_mfma_f32_16x16x32_bf16 v[40:43], v[180:183], v[198:201], v[40:43]
	v_mfma_f32_16x16x32_bf16 v[28:31], v[172:175], v[206:209], v[28:31]
	v_mfma_f32_16x16x32_bf16 v[24:27], v[180:183], v[206:209], v[24:27]
	v_mfma_f32_16x16x32_bf16 v[12:15], v[172:175], v[214:217], v[12:15]
	v_mfma_f32_16x16x32_bf16 v[4:7], v[180:183], v[214:217], v[4:7]
	v_mfma_f32_16x16x32_bf16 v[60:63], v[176:179], v[194:197], v[60:63]
	v_mfma_f32_16x16x32_bf16 v[56:59], v[184:187], v[194:197], v[56:59]
	v_mfma_f32_16x16x32_bf16 v[44:47], v[176:179], v[202:205], v[44:47]
	v_mfma_f32_16x16x32_bf16 v[40:43], v[184:187], v[202:205], v[40:43]
	v_mfma_f32_16x16x32_bf16 v[28:31], v[176:179], v[210:213], v[28:31]
	v_mfma_f32_16x16x32_bf16 v[24:27], v[184:187], v[210:213], v[24:27]
	v_mfma_f32_16x16x32_bf16 v[12:15], v[176:179], v[218:221], v[12:15]
	v_mfma_f32_16x16x32_bf16 v[4:7], v[184:187], v[218:221], v[4:7]
	s_barrier
	s_add_i32 s48, s48, 2
	s_add_u32 s20, s20, 0x100
	s_addc_u32 s21, s21, 0
	s_add_u32 s46, s46, 0x100
	s_addc_u32 s47, s47, 0
	s_cmp_gt_u32 s48, 29
	s_cbranch_scc0 .LBB0_1539
	s_and_b64 vcc, exec, s[8:9]
	s_cbranch_vccz .LBB0_1542
	s_barrier

.LBB0_1624:
	ds_read_b128 v[128:131], v177
	ds_read_b128 v[132:135], v177 offset:1024
	ds_read_b128 v[136:139], v177 offset:2048
	ds_read_b128 v[140:143], v177 offset:3072
	ds_read_b128 v[160:163], v178
	ds_read_b128 v[164:167], v178 offset:1024
	ds_read_b128 v[168:171], v178 offset:2048
	ds_read_b128 v[182:185], v178 offset:3072
	s_add_u32 s20, s18, 0xffea0080
	s_addc_u32 s21, s19, -1
	s_cmpk_eq_i32 s48, 0x54
	s_cselect_b32 s23, s1, s21
	s_cselect_b32 s22, s0, s20
	s_cselect_b32 s21, s17, s47
	s_cselect_b32 s20, s16, s46
	s_add_i32 m0, s27, 0xc000
	ds_read_b128 v[190:193], v179
	ds_read_b128 v[194:197], v179 offset:1024
	ds_read_b128 v[198:201], v179 offset:2048
	ds_read_b128 v[202:205], v179 offset:3072
	ds_read_b128 v[206:209], v179 offset:4096
	ds_read_b128 v[210:213], v179 offset:5120
	ds_read_b128 v[214:217], v179 offset:6144
	ds_read_b128 v[218:221], v179 offset:7168
	global_load_lds_dwordx4 v152, s[18:19]
	s_add_i32 m0, s27, 0xe000
	s_nop 0
	global_load_lds_dwordx4 v154, s[18:19]
	s_waitcnt vmcnt(8)
	s_waitcnt lgkmcnt(0)
	s_barrier
	s_waitcnt lgkmcnt(0)
	v_mfma_f32_16x16x32_bf16 v[124:127], v[128:131], v[190:193], v[124:127]
	v_mfma_f32_16x16x32_bf16 v[120:123], v[136:139], v[190:193], v[120:123]
	v_mfma_f32_16x16x32_bf16 v[108:111], v[128:131], v[198:201], v[108:111]
	v_mfma_f32_16x16x32_bf16 v[104:107], v[136:139], v[198:201], v[104:107]
	v_mfma_f32_16x16x32_bf16 v[92:95], v[128:131], v[206:209], v[92:95]
	v_mfma_f32_16x16x32_bf16 v[88:91], v[136:139], v[206:209], v[88:91]
	v_mfma_f32_16x16x32_bf16 v[76:79], v[128:131], v[214:217], v[76:79]
	v_mfma_f32_16x16x32_bf16 v[72:75], v[136:139], v[214:217], v[72:75]
	v_mfma_f32_16x16x32_bf16 v[124:127], v[132:135], v[194:197], v[124:127]
	v_mfma_f32_16x16x32_bf16 v[120:123], v[140:143], v[194:197], v[120:123]
	v_mfma_f32_16x16x32_bf16 v[108:111], v[132:135], v[202:205], v[108:111]
	v_mfma_f32_16x16x32_bf16 v[104:107], v[140:143], v[202:205], v[104:107]
	v_mfma_f32_16x16x32_bf16 v[92:95], v[132:135], v[210:213], v[92:95]
	v_mfma_f32_16x16x32_bf16 v[88:91], v[140:143], v[210:213], v[88:91]
	v_mfma_f32_16x16x32_bf16 v[76:79], v[132:135], v[218:221], v[76:79]
	v_mfma_f32_16x16x32_bf16 v[72:75], v[140:143], v[218:221], v[72:75]
	v_mfma_f32_16x16x32_bf16 v[116:119], v[160:163], v[190:193], v[116:119]
	v_mfma_f32_16x16x32_bf16 v[112:115], v[168:171], v[190:193], v[112:115]
	v_mfma_f32_16x16x32_bf16 v[100:103], v[160:163], v[198:201], v[100:103]
	v_mfma_f32_16x16x32_bf16 v[96:99], v[168:171], v[198:201], v[96:99]
	v_mfma_f32_16x16x32_bf16 v[84:87], v[160:163], v[206:209], v[84:87]
	v_mfma_f32_16x16x32_bf16 v[80:83], v[168:171], v[206:209], v[80:83]
	v_mfma_f32_16x16x32_bf16 v[68:71], v[160:163], v[214:217], v[68:71]
	v_mfma_f32_16x16x32_bf16 v[64:67], v[168:171], v[214:217], v[64:67]
	v_mfma_f32_16x16x32_bf16 v[116:119], v[164:167], v[194:197], v[116:119]
	v_mfma_f32_16x16x32_bf16 v[112:115], v[182:185], v[194:197], v[112:115]
	v_mfma_f32_16x16x32_bf16 v[100:103], v[164:167], v[202:205], v[100:103]
	v_mfma_f32_16x16x32_bf16 v[96:99], v[182:185], v[202:205], v[96:99]
	v_mfma_f32_16x16x32_bf16 v[84:87], v[164:167], v[210:213], v[84:87]
	v_mfma_f32_16x16x32_bf16 v[80:83], v[182:185], v[210:213], v[80:83]
	v_mfma_f32_16x16x32_bf16 v[68:71], v[164:167], v[218:221], v[68:71]
	v_mfma_f32_16x16x32_bf16 v[64:67], v[182:185], v[218:221], v[64:67]
	s_barrier
	s_add_i32 s49, s39, s26
	s_mov_b32 m0, s49
	ds_read_b128 v[190:193], v179 offset:16384
	ds_read_b128 v[194:197], v179 offset:17408
	ds_read_b128 v[198:201], v179 offset:18432
	ds_read_b128 v[202:205], v179 offset:19456
	ds_read_b128 v[206:209], v179 offset:20480
	ds_read_b128 v[210:213], v179 offset:21504
	ds_read_b128 v[214:217], v179 offset:22528
	ds_read_b128 v[218:221], v179 offset:23552
	global_load_lds_dwordx4 v146, s[20:21]
	s_add_i32 m0, s49, 0x2000
	s_add_u32 s50, s20, 0x160000
	s_addc_u32 s51, s21, 0
	s_add_i32 s49, s40, s26
	global_load_lds_dwordx4 v150, s[20:21]
	s_mov_b32 m0, s49
	s_nop 0
	global_load_lds_dwordx4 v146, s[50:51]
	s_add_i32 m0, s49, 0x2000
	s_nop 0
	global_load_lds_dwordx4 v150, s[50:51]
	s_mov_b32 m0, s27
	s_nop 0
	global_load_lds_dwordx4 v144, s[22:23]
	s_mov_b32 m0, s28
	s_nop 0
	global_load_lds_dwordx4 v148, s[22:23]
	s_waitcnt vmcnt(8)
	s_waitcnt lgkmcnt(0)
	s_barrier
	s_waitcnt lgkmcnt(0)
	v_mfma_f32_16x16x32_bf16 v[60:63], v[128:131], v[190:193], v[60:63]
	v_mfma_f32_16x16x32_bf16 v[56:59], v[136:139], v[190:193], v[56:59]
	v_mfma_f32_16x16x32_bf16 v[44:47], v[128:131], v[198:201], v[44:47]
	v_mfma_f32_16x16x32_bf16 v[40:43], v[136:139], v[198:201], v[40:43]
	v_mfma_f32_16x16x32_bf16 v[28:31], v[128:131], v[206:209], v[28:31]
	v_mfma_f32_16x16x32_bf16 v[24:27], v[136:139], v[206:209], v[24:27]
	v_mfma_f32_16x16x32_bf16 v[12:15], v[128:131], v[214:217], v[12:15]
	v_mfma_f32_16x16x32_bf16 v[8:11], v[136:139], v[214:217], v[8:11]
	v_mfma_f32_16x16x32_bf16 v[60:63], v[132:135], v[194:197], v[60:63]
	v_mfma_f32_16x16x32_bf16 v[56:59], v[140:143], v[194:197], v[56:59]
	v_mfma_f32_16x16x32_bf16 v[44:47], v[132:135], v[202:205], v[44:47]
	v_mfma_f32_16x16x32_bf16 v[40:43], v[140:143], v[202:205], v[40:43]
	v_mfma_f32_16x16x32_bf16 v[28:31], v[132:135], v[210:213], v[28:31]
	v_mfma_f32_16x16x32_bf16 v[24:27], v[140:143], v[210:213], v[24:27]
	v_mfma_f32_16x16x32_bf16 v[12:15], v[132:135], v[218:221], v[12:15]
	v_mfma_f32_16x16x32_bf16 v[8:11], v[140:143], v[218:221], v[8:11]
	v_mfma_f32_16x16x32_bf16 v[52:55], v[160:163], v[190:193], v[52:55]
	v_mfma_f32_16x16x32_bf16 v[48:51], v[168:171], v[190:193], v[48:51]
	v_mfma_f32_16x16x32_bf16 v[36:39], v[160:163], v[198:201], v[36:39]
	v_mfma_f32_16x16x32_bf16 v[32:35], v[168:171], v[198:201], v[32:35]
	v_mfma_f32_16x16x32_bf16 v[20:23], v[160:163], v[206:209], v[20:23]
	v_mfma_f32_16x16x32_bf16 v[16:19], v[168:171], v[206:209], v[16:19]
	v_mfma_f32_16x16x32_bf16 v[4:7], v[160:163], v[214:217], v[4:7]
	v_mfma_f32_16x16x32_bf16 v[0:3], v[168:171], v[214:217], v[0:3]
	v_mfma_f32_16x16x32_bf16 v[52:55], v[164:167], v[194:197], v[52:55]
	v_mfma_f32_16x16x32_bf16 v[48:51], v[182:185], v[194:197], v[48:51]
	v_mfma_f32_16x16x32_bf16 v[36:39], v[164:167], v[202:205], v[36:39]
	v_mfma_f32_16x16x32_bf16 v[32:35], v[182:185], v[202:205], v[32:35]
	v_mfma_f32_16x16x32_bf16 v[20:23], v[164:167], v[210:213], v[20:23]
	v_mfma_f32_16x16x32_bf16 v[16:19], v[182:185], v[210:213], v[16:19]
	v_mfma_f32_16x16x32_bf16 v[4:7], v[164:167], v[218:221], v[4:7]
	v_mfma_f32_16x16x32_bf16 v[0:3], v[182:185], v[218:221], v[0:3]
	s_barrier
	s_add_i32 s49, 0, 0x18000
	s_add_i32 s50, 0, 0x1c000
	v_add_u32_e32 v140, s49, v175
	v_add_u32_e32 v181, s50, v175
	ds_read_b128 v[128:131], v140
	ds_read_b128 v[132:135], v140 offset:1024
	ds_read_b128 v[136:139], v140 offset:2048
	ds_read_b128 v[140:143], v140 offset:3072
	ds_read_b128 v[160:163], v181
	ds_read_b128 v[164:167], v181 offset:1024
	ds_read_b128 v[168:171], v181 offset:2048
	ds_read_b128 v[182:185], v181 offset:3072
	s_add_u32 s22, s22, 0x160000
	s_addc_u32 s23, s23, 0
	s_mov_b32 m0, s29
	ds_read_b128 v[190:193], v179 offset:32768
	ds_read_b128 v[194:197], v179 offset:33792
	ds_read_b128 v[198:201], v179 offset:34816
	ds_read_b128 v[202:205], v179 offset:35840
	ds_read_b128 v[206:209], v179 offset:36864
	ds_read_b128 v[210:213], v179 offset:37888
	ds_read_b128 v[214:217], v179 offset:38912
	ds_read_b128 v[218:221], v179 offset:39936
	global_load_lds_dwordx4 v144, s[22:23]
	s_mov_b32 m0, s30
	s_nop 0
	global_load_lds_dwordx4 v148, s[22:23]
	s_waitcnt vmcnt(8)
	s_waitcnt lgkmcnt(0)
	s_barrier
	s_waitcnt lgkmcnt(0)
	v_mfma_f32_16x16x32_bf16 v[124:127], v[128:131], v[190:193], v[124:127]
	v_mfma_f32_16x16x32_bf16 v[120:123], v[136:139], v[190:193], v[120:123]
	v_mfma_f32_16x16x32_bf16 v[108:111], v[128:131], v[198:201], v[108:111]
	v_mfma_f32_16x16x32_bf16 v[104:107], v[136:139], v[198:201], v[104:107]
	v_mfma_f32_16x16x32_bf16 v[92:95], v[128:131], v[206:209], v[92:95]
	v_mfma_f32_16x16x32_bf16 v[88:91], v[136:139], v[206:209], v[88:91]
	v_mfma_f32_16x16x32_bf16 v[76:79], v[128:131], v[214:217], v[76:79]
	v_mfma_f32_16x16x32_bf16 v[72:75], v[136:139], v[214:217], v[72:75]
	v_mfma_f32_16x16x32_bf16 v[124:127], v[132:135], v[194:197], v[124:127]
	v_mfma_f32_16x16x32_bf16 v[120:123], v[140:143], v[194:197], v[120:123]
	v_mfma_f32_16x16x32_bf16 v[108:111], v[132:135], v[202:205], v[108:111]
	v_mfma_f32_16x16x32_bf16 v[104:107], v[140:143], v[202:205], v[104:107]
	v_mfma_f32_16x16x32_bf16 v[92:95], v[132:135], v[210:213], v[92:95]
	v_mfma_f32_16x16x32_bf16 v[88:91], v[140:143], v[210:213], v[88:91]
	v_mfma_f32_16x16x32_bf16 v[76:79], v[132:135], v[218:221], v[76:79]
	v_mfma_f32_16x16x32_bf16 v[72:75], v[140:143], v[218:221], v[72:75]
	v_mfma_f32_16x16x32_bf16 v[116:119], v[160:163], v[190:193], v[116:119]
	v_mfma_f32_16x16x32_bf16 v[112:115], v[168:171], v[190:193], v[112:115]
	v_mfma_f32_16x16x32_bf16 v[100:103], v[160:163], v[198:201], v[100:103]
	v_mfma_f32_16x16x32_bf16 v[96:99], v[168:171], v[198:201], v[96:99]
	v_mfma_f32_16x16x32_bf16 v[84:87], v[160:163], v[206:209], v[84:87]
	v_mfma_f32_16x16x32_bf16 v[80:83], v[168:171], v[206:209], v[80:83]
	v_mfma_f32_16x16x32_bf16 v[68:71], v[160:163], v[214:217], v[68:71]
	v_mfma_f32_16x16x32_bf16 v[64:67], v[168:171], v[214:217], v[64:67]
	v_mfma_f32_16x16x32_bf16 v[116:119], v[164:167], v[194:197], v[116:119]
	v_mfma_f32_16x16x32_bf16 v[112:115], v[182:185], v[194:197], v[112:115]
	v_mfma_f32_16x16x32_bf16 v[100:103], v[164:167], v[202:205], v[100:103]
	v_mfma_f32_16x16x32_bf16 v[96:99], v[182:185], v[202:205], v[96:99]
	v_mfma_f32_16x16x32_bf16 v[84:87], v[164:167], v[210:213], v[84:87]
	v_mfma_f32_16x16x32_bf16 v[80:83], v[182:185], v[210:213], v[80:83]
	v_mfma_f32_16x16x32_bf16 v[68:71], v[164:167], v[218:221], v[68:71]
	v_mfma_f32_16x16x32_bf16 v[64:67], v[182:185], v[218:221], v[64:67]
	s_barrier
	s_add_u32 s98, s20, 0x80
	s_addc_u32 s99, s21, 0
	s_add_u32 s100, s22, 0xffea0080
	s_addc_u32 s101, s23, -1
	s_add_i32 s22, s49, s26
	s_mov_b32 m0, s22
	ds_read_b128 v[190:193], v179 offset:49152
	ds_read_b128 v[194:197], v179 offset:50176
	ds_read_b128 v[198:201], v179 offset:51200
	ds_read_b128 v[202:205], v179 offset:52224
	ds_read_b128 v[206:209], v179 offset:53248
	ds_read_b128 v[210:213], v179 offset:54272
	ds_read_b128 v[214:217], v179 offset:55296
	ds_read_b128 v[218:221], v179 offset:56320
	global_load_lds_dwordx4 v146, s[98:99]
	s_add_i32 m0, s22, 0x2000
	s_add_u32 s20, s20, 0x160080
	s_addc_u32 s21, s21, 0
	s_add_i32 s22, s50, s26
	global_load_lds_dwordx4 v150, s[98:99]
	s_mov_b32 m0, s22
	s_nop 0
	global_load_lds_dwordx4 v146, s[20:21]
	s_add_i32 m0, s22, 0x2000
	s_nop 0
	global_load_lds_dwordx4 v150, s[20:21]
	s_mov_b32 m0, s35
	s_nop 0
	global_load_lds_dwordx4 v144, s[100:101]
	s_mov_b32 m0, s36
	s_nop 0
	global_load_lds_dwordx4 v148, s[100:101]
	s_waitcnt vmcnt(8)
	s_waitcnt lgkmcnt(0)
	s_barrier
	s_waitcnt lgkmcnt(0)
	v_mfma_f32_16x16x32_bf16 v[60:63], v[128:131], v[190:193], v[60:63]
	v_mfma_f32_16x16x32_bf16 v[56:59], v[136:139], v[190:193], v[56:59]
	v_mfma_f32_16x16x32_bf16 v[44:47], v[128:131], v[198:201], v[44:47]
	v_mfma_f32_16x16x32_bf16 v[40:43], v[136:139], v[198:201], v[40:43]
	v_mfma_f32_16x16x32_bf16 v[28:31], v[128:131], v[206:209], v[28:31]
	v_mfma_f32_16x16x32_bf16 v[24:27], v[136:139], v[206:209], v[24:27]
	v_mfma_f32_16x16x32_bf16 v[12:15], v[128:131], v[214:217], v[12:15]
	v_mfma_f32_16x16x32_bf16 v[8:11], v[136:139], v[214:217], v[8:11]
	v_mfma_f32_16x16x32_bf16 v[60:63], v[132:135], v[194:197], v[60:63]
	v_mfma_f32_16x16x32_bf16 v[56:59], v[140:143], v[194:197], v[56:59]
	v_mfma_f32_16x16x32_bf16 v[44:47], v[132:135], v[202:205], v[44:47]
	v_mfma_f32_16x16x32_bf16 v[40:43], v[140:143], v[202:205], v[40:43]
	v_mfma_f32_16x16x32_bf16 v[28:31], v[132:135], v[210:213], v[28:31]
	v_mfma_f32_16x16x32_bf16 v[24:27], v[140:143], v[210:213], v[24:27]
	v_mfma_f32_16x16x32_bf16 v[12:15], v[132:135], v[218:221], v[12:15]
	v_mfma_f32_16x16x32_bf16 v[8:11], v[140:143], v[218:221], v[8:11]
	v_mfma_f32_16x16x32_bf16 v[52:55], v[160:163], v[190:193], v[52:55]
	v_mfma_f32_16x16x32_bf16 v[48:51], v[168:171], v[190:193], v[48:51]
	v_mfma_f32_16x16x32_bf16 v[36:39], v[160:163], v[198:201], v[36:39]
	v_mfma_f32_16x16x32_bf16 v[32:35], v[168:171], v[198:201], v[32:35]
	v_mfma_f32_16x16x32_bf16 v[20:23], v[160:163], v[206:209], v[20:23]
	v_mfma_f32_16x16x32_bf16 v[16:19], v[168:171], v[206:209], v[16:19]
	v_mfma_f32_16x16x32_bf16 v[4:7], v[160:163], v[214:217], v[4:7]
	v_mfma_f32_16x16x32_bf16 v[0:3], v[168:171], v[214:217], v[0:3]
	v_mfma_f32_16x16x32_bf16 v[52:55], v[164:167], v[194:197], v[52:55]
	v_mfma_f32_16x16x32_bf16 v[48:51], v[182:185], v[194:197], v[48:51]
	v_mfma_f32_16x16x32_bf16 v[36:39], v[164:167], v[202:205], v[36:39]
	v_mfma_f32_16x16x32_bf16 v[32:35], v[182:185], v[202:205], v[32:35]
	v_mfma_f32_16x16x32_bf16 v[20:23], v[164:167], v[210:213], v[20:23]
	v_mfma_f32_16x16x32_bf16 v[16:19], v[182:185], v[210:213], v[16:19]
	v_mfma_f32_16x16x32_bf16 v[4:7], v[164:167], v[218:221], v[4:7]
	v_mfma_f32_16x16x32_bf16 v[0:3], v[182:185], v[218:221], v[0:3]
	s_barrier
	s_add_i32 s48, s48, 2
	s_add_u32 s18, s18, 0x100
	s_addc_u32 s19, s19, 0
	s_add_u32 s46, s46, 0x100
	s_addc_u32 s47, s47, 0
	s_cmpk_gt_u32 s48, 0x55
	s_cbranch_scc0 .LBB0_1624
	s_and_b64 vcc, exec, s[12:13]
	s_cbranch_vccz .LBB0_1627
	s_barrier

	.amdhsa_kernel _Z8yoco_fwd4Args
		.amdhsa_group_segment_fixed_size 0
		.amdhsa_private_segment_fixed_size 0
		.amdhsa_kernarg_size 432
		.amdhsa_user_sgpr_count 2
		.amdhsa_user_sgpr_dispatch_ptr 0
		.amdhsa_user_sgpr_queue_ptr 0
		.amdhsa_user_sgpr_kernarg_segment_ptr 1
		.amdhsa_user_sgpr_dispatch_id 0
		.amdhsa_user_sgpr_kernarg_preload_length 0
		.amdhsa_user_sgpr_kernarg_preload_offset 0
		.amdhsa_user_sgpr_private_segment_size 0
		.amdhsa_uses_dynamic_stack 0
		.amdhsa_enable_private_segment 0
		.amdhsa_system_sgpr_workgroup_id_x 1
		.amdhsa_system_sgpr_workgroup_id_y 0
		.amdhsa_system_sgpr_workgroup_id_z 0
		.amdhsa_system_sgpr_workgroup_info 0
		.amdhsa_system_vgpr_workitem_id 2
		.amdhsa_next_free_vgpr 244
		.amdhsa_next_free_sgpr 102
		.amdhsa_accum_offset 244
		.amdhsa_reserve_vcc 1
		.amdhsa_float_round_mode_32 0
		.amdhsa_float_round_mode_16_64 0
		.amdhsa_float_denorm_mode_32 3
		.amdhsa_float_denorm_mode_16_64 3
		.amdhsa_dx10_clamp 1
		.amdhsa_ieee_mode 1
		.amdhsa_fp16_overflow 0
		.amdhsa_tg_split 0
		.amdhsa_exception_fp_ieee_invalid_op 0
		.amdhsa_exception_fp_denorm_src 0
		.amdhsa_exception_fp_ieee_div_zero 0
		.amdhsa_exception_fp_ieee_overflow 0
		.amdhsa_exception_fp_ieee_underflow 0
		.amdhsa_exception_fp_ieee_inexact 0
		.amdhsa_exception_int_div_zero 0
	.end_amdhsa_kernel

amdhsa.kernels:
  - .agpr_count:     0
    .args:
      - .offset:         0
        .size:           176
        .value_kind:     by_value
      - .offset:         176
        .size:           4
        .value_kind:     hidden_block_count_x
      - .offset:         180
        .size:           4
        .value_kind:     hidden_block_count_y
      - .offset:         184
        .size:           4
        .value_kind:     hidden_block_count_z
      - .offset:         188
        .size:           2
        .value_kind:     hidden_group_size_x
      - .offset:         190
        .size:           2
        .value_kind:     hidden_group_size_y
      - .offset:         192
        .size:           2
        .value_kind:     hidden_group_size_z
      - .offset:         194
        .size:           2
        .value_kind:     hidden_remainder_x
      - .offset:         196
        .size:           2
        .value_kind:     hidden_remainder_y
      - .offset:         198
        .size:           2
        .value_kind:     hidden_remainder_z
      - .offset:         216
        .size:           8
        .value_kind:     hidden_global_offset_x
      - .offset:         224
        .size:           8
        .value_kind:     hidden_global_offset_y
      - .offset:         232
        .size:           8
        .value_kind:     hidden_global_offset_z
      - .offset:         240
        .size:           2
        .value_kind:     hidden_grid_dims
      - .offset:         264
        .size:           8
        .value_kind:     hidden_multigrid_sync_arg
      - .offset:         296
        .size:           4
        .value_kind:     hidden_dynamic_lds_size
    .group_segment_fixed_size: 0
    .kernarg_segment_align: 8
    .kernarg_segment_size: 432
    .language:       OpenCL C
    .language_version:
      - 2
      - 0
    .max_flat_workgroup_size: 512
    .name:           _Z8yoco_fwd4Args
    .private_segment_fixed_size: 0
    .sgpr_count:     108
    .sgpr_spill_count: 130
    .symbol:         _Z8yoco_fwd4Args.kd
    .uniform_work_group_size: 1
    .uses_dynamic_stack: false
    .vgpr_count:     244
    .vgpr_spill_count: 0
    .wavefront_size: 64
